# prompt attention q-tile loop: QK (4 of 5 key tiles) and PV (4 groups) LDS fragment reads double-buffered (read issued before the previous MFMA's wait) on top of p7a
# speedup vs baseline: 1.0009x; 1.0009x over previous
; #define GAS __attribute__((address_space(1)))
; #define LAS __attribute__((address_space(3)))
; template <int NT>
; __device__ __forceinline__ void attn_qtile(const LAS unsigned char* lds, int ktile0, const bf16x8 (&Q)[8], int r, int kmin, int kmax, int g, float sink, bf16* orow, int lane) {
;     ...
;     for (int t = 0; t < NT; ++t) {
; #pragma unroll
;         for (int i = 0; i < 16; ++i) X[t][i] = 0.f;
; #pragma unroll
;         for (int ks = 0; ks < 8; ++ks) { const bf16x8 kf = *(const LAS bf16x8*)(lds + K_OFF + (32 * (ktile0 + t) + c) * KROW + (16 * ks + 8 * h) * 2);
;             X[t] = __builtin_amdgcn_mfma_f32_32x32x16_bf16(kf, Q[ks], X[t], 0, 0, 0); }
;     }
; __device__ __forceinline__ void prompt_unit(Frame& F, const Args& A, int b, int hk) {
;     ...
;     for (int qt = 0; qt < 2; ++qt) { const int r = 64 * half + 32 * qt + c, row = 128 * b + r;
;         bf16x8 Q[8];
; #pragma unroll
;         for (int ks = 0; ks < 8; ++ks) Q[ks] = *(const GAS bf16x8*)(PROJ + (size_t)row * NPROJ + 128 * head + 16 * ks + 8 * h);
;         attn_qtile<5>(lds, 2 * half + qt, Q, r, b == 0 ? 128 : 0, 256, g, sink, MIX + (size_t)row * D + 128 * head, F.lane);
.LBB0_625:
	v_lshl_or_b32 v187, s0, 5, v125
	v_or_b32_e32 v186, s72, v187
	v_mul_u32_u24_e32 v110, 0x2400, v186
	v_lshl_add_u64 v[6:7], v[110:111], 1, v[144:145]
	global_load_dwordx4 v[2:5], v[6:7], off
	global_load_dwordx4 v[106:109], v[6:7], off offset:32
	global_load_dwordx4 v[102:105], v[6:7], off offset:64
	global_load_dwordx4 v[98:101], v[6:7], off offset:96
	global_load_dwordx4 v[94:97], v[6:7], off offset:128
	global_load_dwordx4 v[90:93], v[6:7], off offset:160
	global_load_dwordx4 v[86:89], v[6:7], off offset:192
	global_load_dwordx4 v[82:85], v[6:7], off offset:224
	s_or_b32 s34, s0, s16
	s_lshl_b32 s6, s34, 5
	v_or_b32_e32 v6, s6, v150
	v_mad_u32_u24 v14, v6, s14, v148
	ds_read_b128 v[6:9], v14
	ds_read_b128 v[10:13], v14 offset:32
	s_add_i32 s13, s34, 1
	s_lshl_b32 s27, s13, 5
	s_add_i32 s8, s34, 2
	s_lshl_b32 s26, s8, 5
	s_add_i32 s1, s34, 3
	s_lshl_b32 s74, s1, 5
	s_or_b32 s0, s34, 4
	s_lshl_b32 s73, s0, 5
	s_waitcnt vmcnt(7) lgkmcnt(1)
	v_mfma_f32_32x32x16_bf16 v[66:81], v[6:9], v[2:5], 0
	ds_read_b128 v[6:9], v14 offset:64
	s_waitcnt vmcnt(6) lgkmcnt(1)
	v_mfma_f32_32x32x16_bf16 v[66:81], v[10:13], v[106:109], v[66:81]
	ds_read_b128 v[10:13], v14 offset:96
	s_waitcnt vmcnt(5) lgkmcnt(1)
	v_mfma_f32_32x32x16_bf16 v[66:81], v[6:9], v[102:105], v[66:81]
	ds_read_b128 v[6:9], v14 offset:128
	s_waitcnt vmcnt(4) lgkmcnt(1)
	v_mfma_f32_32x32x16_bf16 v[66:81], v[10:13], v[98:101], v[66:81]
	ds_read_b128 v[10:13], v14 offset:160
	s_waitcnt vmcnt(3) lgkmcnt(1)
	v_mfma_f32_32x32x16_bf16 v[66:81], v[6:9], v[94:97], v[66:81]
	ds_read_b128 v[6:9], v14 offset:192
	s_waitcnt vmcnt(2) lgkmcnt(1)
	v_mfma_f32_32x32x16_bf16 v[66:81], v[10:13], v[90:93], v[66:81]
	ds_read_b128 v[10:13], v14 offset:224
	s_waitcnt vmcnt(1) lgkmcnt(1)
	v_mfma_f32_32x32x16_bf16 v[66:81], v[6:9], v[86:89], v[66:81]
	s_waitcnt vmcnt(0) lgkmcnt(0)
	v_mfma_f32_32x32x16_bf16 v[66:81], v[10:13], v[82:85], v[66:81]
	v_or_b32_e32 v6, s27, v150
	v_mad_u32_u24 v14, v6, s14, v148
	ds_read_b128 v[6:9], v14
	ds_read_b128 v[10:13], v14 offset:32
	s_waitcnt lgkmcnt(1)
	v_mfma_f32_32x32x16_bf16 v[50:65], v[6:9], v[2:5], 0
	ds_read_b128 v[6:9], v14 offset:64
	s_waitcnt lgkmcnt(1)
	v_mfma_f32_32x32x16_bf16 v[50:65], v[10:13], v[106:109], v[50:65]
	ds_read_b128 v[10:13], v14 offset:96
	s_waitcnt lgkmcnt(1)
	v_mfma_f32_32x32x16_bf16 v[50:65], v[6:9], v[102:105], v[50:65]
	ds_read_b128 v[6:9], v14 offset:128
	s_waitcnt lgkmcnt(1)
	v_mfma_f32_32x32x16_bf16 v[50:65], v[10:13], v[98:101], v[50:65]
	ds_read_b128 v[10:13], v14 offset:160
	s_waitcnt lgkmcnt(1)
	v_mfma_f32_32x32x16_bf16 v[50:65], v[6:9], v[94:97], v[50:65]
	ds_read_b128 v[6:9], v14 offset:192
	s_waitcnt lgkmcnt(1)
	v_mfma_f32_32x32x16_bf16 v[50:65], v[10:13], v[90:93], v[50:65]
	ds_read_b128 v[10:13], v14 offset:224
	s_waitcnt lgkmcnt(1)
	v_mfma_f32_32x32x16_bf16 v[50:65], v[6:9], v[86:89], v[50:65]
	s_waitcnt lgkmcnt(0)
	v_mfma_f32_32x32x16_bf16 v[50:65], v[10:13], v[82:85], v[50:65]
	v_or_b32_e32 v6, s26, v150
	v_mad_u32_u24 v14, v6, s14, v148
	ds_read_b128 v[6:9], v14
	ds_read_b128 v[10:13], v14 offset:32
	s_waitcnt lgkmcnt(1)
	v_mfma_f32_32x32x16_bf16 v[34:49], v[6:9], v[2:5], 0
	ds_read_b128 v[6:9], v14 offset:64
	s_waitcnt lgkmcnt(1)
	v_mfma_f32_32x32x16_bf16 v[34:49], v[10:13], v[106:109], v[34:49]
	ds_read_b128 v[10:13], v14 offset:96
	s_waitcnt lgkmcnt(1)
	v_mfma_f32_32x32x16_bf16 v[34:49], v[6:9], v[102:105], v[34:49]
	ds_read_b128 v[6:9], v14 offset:128
	s_waitcnt lgkmcnt(1)
	v_mfma_f32_32x32x16_bf16 v[34:49], v[10:13], v[98:101], v[34:49]
	ds_read_b128 v[10:13], v14 offset:160
	s_waitcnt lgkmcnt(1)
	v_mfma_f32_32x32x16_bf16 v[34:49], v[6:9], v[94:97], v[34:49]
	ds_read_b128 v[6:9], v14 offset:192
	s_waitcnt lgkmcnt(1)
	v_mfma_f32_32x32x16_bf16 v[34:49], v[10:13], v[90:93], v[34:49]
	ds_read_b128 v[10:13], v14 offset:224
	s_waitcnt lgkmcnt(1)
	v_mfma_f32_32x32x16_bf16 v[34:49], v[6:9], v[86:89], v[34:49]
	s_waitcnt lgkmcnt(0)
	v_mfma_f32_32x32x16_bf16 v[34:49], v[10:13], v[82:85], v[34:49]
	v_or_b32_e32 v6, s74, v150
	v_mad_u32_u24 v14, v6, s14, v148
	ds_read_b128 v[6:9], v14
	ds_read_b128 v[10:13], v14 offset:32
	s_waitcnt lgkmcnt(1)
	v_mfma_f32_32x32x16_bf16 v[18:33], v[6:9], v[2:5], 0
	ds_read_b128 v[6:9], v14 offset:64
	s_waitcnt lgkmcnt(1)
	v_mfma_f32_32x32x16_bf16 v[18:33], v[10:13], v[106:109], v[18:33]
	ds_read_b128 v[10:13], v14 offset:96
	s_waitcnt lgkmcnt(1)
	v_mfma_f32_32x32x16_bf16 v[18:33], v[6:9], v[102:105], v[18:33]
	ds_read_b128 v[6:9], v14 offset:128
	s_waitcnt lgkmcnt(1)
	v_mfma_f32_32x32x16_bf16 v[18:33], v[10:13], v[98:101], v[18:33]
	ds_read_b128 v[10:13], v14 offset:160
	s_waitcnt lgkmcnt(1)
	v_mfma_f32_32x32x16_bf16 v[18:33], v[6:9], v[94:97], v[18:33]
	ds_read_b128 v[6:9], v14 offset:192
	s_waitcnt lgkmcnt(1)
	v_mfma_f32_32x32x16_bf16 v[18:33], v[10:13], v[90:93], v[18:33]
	ds_read_b128 v[10:13], v14 offset:224
	s_waitcnt lgkmcnt(1)
	v_mfma_f32_32x32x16_bf16 v[18:33], v[6:9], v[86:89], v[18:33]
	s_waitcnt lgkmcnt(0)
	v_mfma_f32_32x32x16_bf16 v[18:33], v[10:13], v[82:85], v[18:33]
	v_or_b32_e32 v6, s73, v150
	v_mad_u32_u24 v110, v6, s14, v148
	ds_read_b128 v[6:9], v110
	ds_read_b128 v[188:191], v110 offset:32
	s_waitcnt lgkmcnt(1)
	v_mfma_f32_32x32x16_bf16 v[2:17], v[6:9], v[2:5], 0
	s_waitcnt lgkmcnt(0)
	v_mfma_f32_32x32x16_bf16 v[2:17], v[188:191], v[106:109], v[2:17]
	ds_read_b128 v[106:109], v110 offset:64
	s_waitcnt lgkmcnt(0)
	v_mfma_f32_32x32x16_bf16 v[2:17], v[106:109], v[102:105], v[2:17]
	ds_read_b128 v[102:105], v110 offset:96
	s_waitcnt lgkmcnt(0)
	v_mfma_f32_32x32x16_bf16 v[2:17], v[102:105], v[98:101], v[2:17]
	ds_read_b128 v[98:101], v110 offset:128
	s_waitcnt lgkmcnt(0)
; #define LAS __attribute__((address_space(3)))
; template <int NT>
; __device__ __forceinline__ void attn_qtile(const LAS unsigned char* lds, int ktile0, const bf16x8 (&Q)[8], int r, int kmin, int kmax, int g, float sink, bf16* orow, int lane) {
;     ...
;     const LAS float* lut = (const LAS float*)(lds + LUT_OFF) + g * LUT_STRIDE;
;     float mx = sink;
; #pragma unroll
;     for (int t = 0; t < NT; ++t)
; #pragma unroll
;         for (int i = 0; i < 16; ++i) { const int kidx = 32 * (ktile0 + t) + (i & 3) + 8 * (i >> 2) + 4 * h; const int dist = 128 + r - kidx;
;             const bool valid = (dist >= 0) && (dist <= 128) && (kidx >= kmin) && (kidx < kmax);
;             const int di = dist < 0 ? 0 : (dist > 128 ? 128 : dist);
;             float s = X[t][i] * SCALE + lut[di]; s = valid ? s : -1e30f; X[t][i] = s; mx = fmaxf(mx, s); }
	v_mfma_f32_32x32x16_bf16 v[2:17], v[98:101], v[94:97], v[2:17]
	ds_read_b128 v[94:97], v110 offset:160
	s_waitcnt lgkmcnt(0)
	v_mfma_f32_32x32x16_bf16 v[2:17], v[94:97], v[90:93], v[2:17]
	ds_read_b128 v[90:93], v110 offset:192
	s_waitcnt lgkmcnt(0)
	v_mfma_f32_32x32x16_bf16 v[2:17], v[90:93], v[86:89], v[2:17]
	ds_read_b128 v[86:89], v110 offset:224
	s_waitcnt lgkmcnt(0)
	v_mfma_f32_32x32x16_bf16 v[2:17], v[86:89], v[82:85], v[2:17]
	v_or_b32_e32 v82, 0x80, v187
	v_or_b32_e32 v83, s6, v149
	v_sub_u32_e32 v84, v82, v83
	v_cmp_gt_u32_e32 vcc, s19, v84
	v_min_u32_e32 v84, 0x80, v84
	v_lshl_add_u32 v84, v84, 2, s17
	ds_read_b32 v84, v84
	v_cmp_le_u32_e64 s[6:7], s12, v83
	s_and_b64 vcc, s[6:7], vcc
	s_waitcnt lgkmcnt(0)
	v_fmac_f32_e32 v84, 0x3db504f3, v66
	v_cndmask_b32_e32 v66, v183, v84, vcc
	v_or_b32_e32 v84, 1, v83
	v_sub_u32_e32 v85, v82, v84
	v_cmp_gt_u32_e32 vcc, s19, v85
	v_cmp_le_u32_e64 s[6:7], s12, v84
	v_min_u32_e32 v84, 0x80, v85
	v_or_b32_e32 v85, 2, v83
	v_lshl_add_u32 v84, v84, 2, s17
	v_sub_u32_e32 v86, v82, v85
	s_and_b64 vcc, s[6:7], vcc
	ds_read_b32 v84, v84
	v_cmp_le_u32_e64 s[6:7], s12, v85
	v_min_u32_e32 v85, 0x80, v86
	v_lshl_add_u32 v85, v85, 2, s17
	ds_read_b32 v85, v85
	s_waitcnt lgkmcnt(1)
	v_fmac_f32_e32 v84, 0x3db504f3, v67
	v_cndmask_b32_e32 v67, v183, v84, vcc
	v_cmp_gt_u32_e32 vcc, s19, v86
	s_and_b64 vcc, s[6:7], vcc
	s_waitcnt lgkmcnt(0)
	v_fmac_f32_e32 v85, 0x3db504f3, v68
	v_cndmask_b32_e32 v68, v183, v85, vcc
	v_or_b32_e32 v85, 3, v83
	v_sub_u32_e32 v86, v82, v85
	v_cmp_le_u32_e64 s[6:7], s12, v85
	v_min_u32_e32 v85, 0x80, v86
	v_lshl_add_u32 v85, v85, 2, s17
	ds_read_b32 v85, v85
	v_cmp_gt_u32_e32 vcc, s19, v86
	s_and_b64 vcc, s[6:7], vcc
	v_max3_f32 v84, v185, v66, v67
	s_waitcnt lgkmcnt(0)
	v_fmac_f32_e32 v85, 0x3db504f3, v69
	v_cndmask_b32_e32 v69, v183, v85, vcc
	v_or_b32_e32 v85, 8, v83
	v_sub_u32_e32 v86, v82, v85
	v_cmp_le_u32_e64 s[6:7], s12, v85
	v_min_u32_e32 v85, 0x80, v86
	v_lshl_add_u32 v85, v85, 2, s17
	ds_read_b32 v85, v85
	v_cmp_gt_u32_e32 vcc, s19, v86
	s_and_b64 vcc, s[6:7], vcc
	v_max3_f32 v84, v84, v68, v69
	s_waitcnt lgkmcnt(0)
	v_fmac_f32_e32 v85, 0x3db504f3, v70
	v_cndmask_b32_e32 v70, v183, v85, vcc
	v_or_b32_e32 v85, 9, v83
	v_sub_u32_e32 v86, v82, v85
	v_cmp_le_u32_e64 s[6:7], s12, v85
	v_min_u32_e32 v85, 0x80, v86
	v_lshl_add_u32 v85, v85, 2, s17
	ds_read_b32 v85, v85
	v_cmp_gt_u32_e32 vcc, s19, v86
	s_and_b64 vcc, s[6:7], vcc
	s_waitcnt lgkmcnt(0)
	v_fmac_f32_e32 v85, 0x3db504f3, v71
	v_cndmask_b32_e32 v71, v183, v85, vcc
	v_or_b32_e32 v85, 10, v83
	v_sub_u32_e32 v86, v82, v85
	v_cmp_le_u32_e64 s[6:7], s12, v85
	v_min_u32_e32 v85, 0x80, v86
	v_lshl_add_u32 v85, v85, 2, s17
	ds_read_b32 v85, v85
	v_cmp_gt_u32_e32 vcc, s19, v86
	s_and_b64 vcc, s[6:7], vcc
	v_max3_f32 v84, v84, v70, v71
	s_waitcnt lgkmcnt(0)
	v_fmac_f32_e32 v85, 0x3db504f3, v72
	v_cndmask_b32_e32 v72, v183, v85, vcc
	v_or_b32_e32 v85, 11, v83
	v_sub_u32_e32 v86, v82, v85
	v_cmp_le_u32_e64 s[6:7], s12, v85
	v_min_u32_e32 v85, 0x80, v86
	v_lshl_add_u32 v85, v85, 2, s17
	ds_read_b32 v85, v85
	v_cmp_gt_u32_e32 vcc, s19, v86
	s_and_b64 vcc, s[6:7], vcc
	s_waitcnt lgkmcnt(0)
	v_fmac_f32_e32 v85, 0x3db504f3, v73
	v_cndmask_b32_e32 v73, v183, v85, vcc
	v_or_b32_e32 v85, 16, v83
	v_sub_u32_e32 v86, v82, v85
	v_cmp_le_u32_e64 s[6:7], s12, v85
	v_min_u32_e32 v85, 0x80, v86
	v_lshl_add_u32 v85, v85, 2, s17
	ds_read_b32 v85, v85
	v_cmp_gt_u32_e32 vcc, s19, v86
	s_and_b64 vcc, s[6:7], vcc
	v_max3_f32 v84, v84, v72, v73
	s_waitcnt lgkmcnt(0)
	v_fmac_f32_e32 v85, 0x3db504f3, v74
	v_cndmask_b32_e32 v74, v183, v85, vcc
	v_or_b32_e32 v85, 17, v83
	v_sub_u32_e32 v86, v82, v85
	v_cmp_le_u32_e64 s[6:7], s12, v85
	v_min_u32_e32 v85, 0x80, v86
	v_lshl_add_u32 v85, v85, 2, s17
	ds_read_b32 v85, v85
	v_cmp_gt_u32_e32 vcc, s19, v86
	s_and_b64 vcc, s[6:7], vcc
	s_waitcnt lgkmcnt(0)
	v_fmac_f32_e32 v85, 0x3db504f3, v75
	v_cndmask_b32_e32 v75, v183, v85, vcc
	v_or_b32_e32 v85, 18, v83
	v_sub_u32_e32 v86, v82, v85
	v_cmp_le_u32_e64 s[6:7], s12, v85
	v_min_u32_e32 v85, 0x80, v86
	v_lshl_add_u32 v85, v85, 2, s17
	ds_read_b32 v85, v85
	v_cmp_gt_u32_e32 vcc, s19, v86
	s_and_b64 vcc, s[6:7], vcc
	v_max3_f32 v84, v84, v74, v75
	s_waitcnt lgkmcnt(0)
	v_fmac_f32_e32 v85, 0x3db504f3, v76
	v_cndmask_b32_e32 v76, v183, v85, vcc
	v_or_b32_e32 v85, 19, v83
	v_sub_u32_e32 v86, v82, v85
	v_cmp_le_u32_e64 s[6:7], s12, v85
	v_min_u32_e32 v85, 0x80, v86
	v_lshl_add_u32 v85, v85, 2, s17
	ds_read_b32 v85, v85
	v_cmp_gt_u32_e32 vcc, s19, v86
	s_and_b64 vcc, s[6:7], vcc
	s_waitcnt lgkmcnt(0)
	v_fmac_f32_e32 v85, 0x3db504f3, v77
	v_cndmask_b32_e32 v77, v183, v85, vcc
	v_or_b32_e32 v85, 24, v83
	v_sub_u32_e32 v86, v82, v85
	v_cmp_le_u32_e64 s[6:7], s12, v85
	v_min_u32_e32 v85, 0x80, v86
	v_lshl_add_u32 v85, v85, 2, s17
	ds_read_b32 v85, v85
	v_cmp_gt_u32_e32 vcc, s19, v86
	s_and_b64 vcc, s[6:7], vcc
	v_max3_f32 v84, v84, v76, v77
	s_waitcnt lgkmcnt(0)
	v_fmac_f32_e32 v85, 0x3db504f3, v78
	v_cndmask_b32_e32 v78, v183, v85, vcc
	v_or_b32_e32 v85, 25, v83
	v_sub_u32_e32 v86, v82, v85
	v_cmp_le_u32_e64 s[6:7], s12, v85
	v_min_u32_e32 v85, 0x80, v86
	v_lshl_add_u32 v85, v85, 2, s17
	ds_read_b32 v85, v85
	v_cmp_gt_u32_e32 vcc, s19, v86
	s_and_b64 vcc, s[6:7], vcc
	s_waitcnt lgkmcnt(0)
	v_fmac_f32_e32 v85, 0x3db504f3, v79
	v_cndmask_b32_e32 v79, v183, v85, vcc
	v_or_b32_e32 v85, 26, v83
	v_sub_u32_e32 v86, v82, v85
	v_cmp_le_u32_e64 s[6:7], s12, v85
	v_min_u32_e32 v85, 0x80, v86
	v_lshl_add_u32 v85, v85, 2, s17
	ds_read_b32 v85, v85
	v_cmp_gt_u32_e32 vcc, s19, v86
	s_and_b64 vcc, s[6:7], vcc
	v_or_b32_e32 v83, 27, v83
	v_cmp_le_u32_e64 s[6:7], s12, v83
	s_waitcnt lgkmcnt(0)
; template <int NT>
; __device__ __forceinline__ void attn_qtile(const LAS unsigned char* lds, int ktile0, const bf16x8 (&Q)[8], int r, int kmin, int kmax, int g, float sink, bf16* orow, int lane) {
;     ...
;     for (int t = 0; t < NT; ++t)
; #pragma unroll
;         for (int i = 0; i < 16; ++i) { const int kidx = 32 * (ktile0 + t) + (i & 3) + 8 * (i >> 2) + 4 * h; const int dist = 128 + r - kidx;
;             const bool valid = (dist >= 0) && (dist <= 128) && (kidx >= kmin) && (kidx < kmax);
;             const int di = dist < 0 ? 0 : (dist > 128 ? 128 : dist);
;             float s = X[t][i] * SCALE + lut[di]; s = valid ? s : -1e30f; X[t][i] = s; mx = fmaxf(mx, s); }
	v_fmac_f32_e32 v85, 0x3db504f3, v80
	v_cndmask_b32_e32 v80, v183, v85, vcc
	v_sub_u32_e32 v85, v82, v83
	v_min_u32_e32 v83, 0x80, v85
	v_lshl_add_u32 v83, v83, 2, s17
	ds_read_b32 v83, v83
	v_cmp_gt_u32_e32 vcc, s19, v85
	s_and_b64 vcc, s[6:7], vcc
	v_max3_f32 v84, v84, v78, v79
	s_waitcnt lgkmcnt(0)
	v_fmac_f32_e32 v83, 0x3db504f3, v81
	v_cndmask_b32_e32 v81, v183, v83, vcc
	v_max3_f32 v83, v84, v80, v81
	v_or_b32_e32 v84, s27, v149
	v_sub_u32_e32 v85, v82, v84
	v_cmp_gt_u32_e32 vcc, s19, v85
	v_med3_i32 v85, v85, 0, v156
	v_lshl_add_u32 v85, v85, 2, s17
	ds_read_b32 v85, v85
	v_cmp_le_u32_e64 s[6:7], s12, v84
	s_and_b64 vcc, s[6:7], vcc
	s_waitcnt lgkmcnt(0)
	v_fmac_f32_e32 v85, 0x3db504f3, v50
	v_cndmask_b32_e32 v50, v183, v85, vcc
	v_or_b32_e32 v85, 1, v84
	v_sub_u32_e32 v86, v82, v85
	v_cmp_le_u32_e64 s[6:7], s12, v85
	v_med3_i32 v85, v86, 0, v156
	v_lshl_add_u32 v85, v85, 2, s17
	ds_read_b32 v85, v85
	v_cmp_gt_u32_e32 vcc, s19, v86
	s_and_b64 vcc, s[6:7], vcc
	s_waitcnt lgkmcnt(0)
	v_fmac_f32_e32 v85, 0x3db504f3, v51
	v_cndmask_b32_e32 v51, v183, v85, vcc
	v_or_b32_e32 v85, 2, v84
	v_sub_u32_e32 v86, v82, v85
	v_cmp_le_u32_e64 s[6:7], s12, v85
	v_med3_i32 v85, v86, 0, v156
	v_lshl_add_u32 v85, v85, 2, s17
	ds_read_b32 v85, v85
	v_cmp_gt_u32_e32 vcc, s19, v86
	s_and_b64 vcc, s[6:7], vcc
	v_max3_f32 v83, v83, v50, v51
	s_waitcnt lgkmcnt(0)
	v_fmac_f32_e32 v85, 0x3db504f3, v52
	v_cndmask_b32_e32 v52, v183, v85, vcc
	v_or_b32_e32 v85, 3, v84
	v_sub_u32_e32 v86, v82, v85
	v_cmp_le_u32_e64 s[6:7], s12, v85
	v_med3_i32 v85, v86, 0, v156
	v_lshl_add_u32 v85, v85, 2, s17
	ds_read_b32 v85, v85
	v_cmp_gt_u32_e32 vcc, s19, v86
	s_and_b64 vcc, s[6:7], vcc
	s_waitcnt lgkmcnt(0)
	v_fmac_f32_e32 v85, 0x3db504f3, v53
	v_cndmask_b32_e32 v53, v183, v85, vcc
	v_or_b32_e32 v85, 8, v84
	v_sub_u32_e32 v86, v82, v85
	v_cmp_le_u32_e64 s[6:7], s12, v85
	v_med3_i32 v85, v86, 0, v156
	v_lshl_add_u32 v85, v85, 2, s17
	ds_read_b32 v85, v85
	v_cmp_gt_u32_e32 vcc, s19, v86
	s_and_b64 vcc, s[6:7], vcc
	v_max3_f32 v83, v83, v52, v53
	s_waitcnt lgkmcnt(0)
	v_fmac_f32_e32 v85, 0x3db504f3, v54
	v_cndmask_b32_e32 v54, v183, v85, vcc
	v_or_b32_e32 v85, 9, v84
	v_sub_u32_e32 v86, v82, v85
	v_cmp_le_u32_e64 s[6:7], s12, v85
	v_med3_i32 v85, v86, 0, v156
	v_lshl_add_u32 v85, v85, 2, s17
	ds_read_b32 v85, v85
	v_cmp_gt_u32_e32 vcc, s19, v86
	s_and_b64 vcc, s[6:7], vcc
	s_waitcnt lgkmcnt(0)
	v_fmac_f32_e32 v85, 0x3db504f3, v55
	v_cndmask_b32_e32 v55, v183, v85, vcc
	v_or_b32_e32 v85, 10, v84
	v_sub_u32_e32 v86, v82, v85
	v_cmp_le_u32_e64 s[6:7], s12, v85
	v_med3_i32 v85, v86, 0, v156
	v_lshl_add_u32 v85, v85, 2, s17
	ds_read_b32 v85, v85
	v_cmp_gt_u32_e32 vcc, s19, v86
	s_and_b64 vcc, s[6:7], vcc
	v_max3_f32 v83, v83, v54, v55
	s_waitcnt lgkmcnt(0)
	v_fmac_f32_e32 v85, 0x3db504f3, v56
	v_cndmask_b32_e32 v56, v183, v85, vcc
	v_or_b32_e32 v85, 11, v84
	v_sub_u32_e32 v86, v82, v85
	v_cmp_le_u32_e64 s[6:7], s12, v85
	v_med3_i32 v85, v86, 0, v156
	v_lshl_add_u32 v85, v85, 2, s17
	ds_read_b32 v85, v85
	v_cmp_gt_u32_e32 vcc, s19, v86
	s_and_b64 vcc, s[6:7], vcc
	s_waitcnt lgkmcnt(0)
	v_fmac_f32_e32 v85, 0x3db504f3, v57
	v_cndmask_b32_e32 v57, v183, v85, vcc
	v_or_b32_e32 v85, 16, v84
	v_sub_u32_e32 v86, v82, v85
	v_cmp_le_u32_e64 s[6:7], s12, v85
	v_med3_i32 v85, v86, 0, v156
	v_lshl_add_u32 v85, v85, 2, s17
	ds_read_b32 v85, v85
	v_cmp_gt_u32_e32 vcc, s19, v86
	s_and_b64 vcc, s[6:7], vcc
	v_max3_f32 v83, v83, v56, v57
	s_waitcnt lgkmcnt(0)
	v_fmac_f32_e32 v85, 0x3db504f3, v58
	v_cndmask_b32_e32 v58, v183, v85, vcc
	v_or_b32_e32 v85, 17, v84
	v_sub_u32_e32 v86, v82, v85
	v_cmp_le_u32_e64 s[6:7], s12, v85
	v_med3_i32 v85, v86, 0, v156
	v_lshl_add_u32 v85, v85, 2, s17
	ds_read_b32 v85, v85
	v_cmp_gt_u32_e32 vcc, s19, v86
	s_and_b64 vcc, s[6:7], vcc
	s_waitcnt lgkmcnt(0)
	v_fmac_f32_e32 v85, 0x3db504f3, v59
	v_cndmask_b32_e32 v59, v183, v85, vcc
	v_or_b32_e32 v85, 18, v84
	v_sub_u32_e32 v86, v82, v85
	v_cmp_le_u32_e64 s[6:7], s12, v85
	v_med3_i32 v85, v86, 0, v156
	v_lshl_add_u32 v85, v85, 2, s17
	ds_read_b32 v85, v85
	v_cmp_gt_u32_e32 vcc, s19, v86
	s_and_b64 vcc, s[6:7], vcc
	v_max3_f32 v83, v83, v58, v59
	s_waitcnt lgkmcnt(0)
	v_fmac_f32_e32 v85, 0x3db504f3, v60
	v_cndmask_b32_e32 v60, v183, v85, vcc
	v_or_b32_e32 v85, 19, v84
	v_sub_u32_e32 v86, v82, v85
	v_cmp_le_u32_e64 s[6:7], s12, v85
	v_med3_i32 v85, v86, 0, v156
	v_lshl_add_u32 v85, v85, 2, s17
	ds_read_b32 v85, v85
	v_cmp_gt_u32_e32 vcc, s19, v86
	s_and_b64 vcc, s[6:7], vcc
	s_waitcnt lgkmcnt(0)
	v_fmac_f32_e32 v85, 0x3db504f3, v61
	v_cndmask_b32_e32 v61, v183, v85, vcc
	v_or_b32_e32 v85, 24, v84
	v_sub_u32_e32 v86, v82, v85
	v_cmp_le_u32_e64 s[6:7], s12, v85
	v_med3_i32 v85, v86, 0, v156
	v_lshl_add_u32 v85, v85, 2, s17
	ds_read_b32 v85, v85
	v_cmp_gt_u32_e32 vcc, s19, v86
	s_and_b64 vcc, s[6:7], vcc
	v_max3_f32 v83, v83, v60, v61
	s_waitcnt lgkmcnt(0)
	v_fmac_f32_e32 v85, 0x3db504f3, v62
	v_cndmask_b32_e32 v62, v183, v85, vcc
	v_or_b32_e32 v85, 25, v84
	v_sub_u32_e32 v86, v82, v85
	v_cmp_le_u32_e64 s[6:7], s12, v85
	v_med3_i32 v85, v86, 0, v156
	v_lshl_add_u32 v85, v85, 2, s17
	ds_read_b32 v85, v85
	v_cmp_gt_u32_e32 vcc, s19, v86
	s_and_b64 vcc, s[6:7], vcc
	s_waitcnt lgkmcnt(0)
	v_fmac_f32_e32 v85, 0x3db504f3, v63
	v_cndmask_b32_e32 v63, v183, v85, vcc
	v_or_b32_e32 v85, 26, v84
	v_sub_u32_e32 v86, v82, v85
	v_cmp_le_u32_e64 s[6:7], s12, v85
	v_med3_i32 v85, v86, 0, v156
	v_lshl_add_u32 v85, v85, 2, s17
	ds_read_b32 v85, v85
	v_cmp_gt_u32_e32 vcc, s19, v86
	s_and_b64 vcc, s[6:7], vcc
	v_or_b32_e32 v84, 27, v84
	v_cmp_le_u32_e64 s[6:7], s12, v84
	s_waitcnt lgkmcnt(0)
; template <int NT>
; __device__ __forceinline__ void attn_qtile(const LAS unsigned char* lds, int ktile0, const bf16x8 (&Q)[8], int r, int kmin, int kmax, int g, float sink, bf16* orow, int lane) {
;     ...
;     for (int t = 0; t < NT; ++t)
; #pragma unroll
;         for (int i = 0; i < 16; ++i) { const int kidx = 32 * (ktile0 + t) + (i & 3) + 8 * (i >> 2) + 4 * h; const int dist = 128 + r - kidx;
;             const bool valid = (dist >= 0) && (dist <= 128) && (kidx >= kmin) && (kidx < kmax);
;             const int di = dist < 0 ? 0 : (dist > 128 ? 128 : dist);
;             float s = X[t][i] * SCALE + lut[di]; s = valid ? s : -1e30f; X[t][i] = s; mx = fmaxf(mx, s); }
	v_fmac_f32_e32 v85, 0x3db504f3, v64
	v_cndmask_b32_e32 v64, v183, v85, vcc
	v_sub_u32_e32 v85, v82, v84
	v_med3_i32 v84, v85, 0, v156
	v_lshl_add_u32 v84, v84, 2, s17
	ds_read_b32 v84, v84
	v_cmp_gt_u32_e32 vcc, s19, v85
	s_and_b64 vcc, s[6:7], vcc
	v_max3_f32 v83, v83, v62, v63
	s_waitcnt lgkmcnt(0)
	v_fmac_f32_e32 v84, 0x3db504f3, v65
	v_cndmask_b32_e32 v65, v183, v84, vcc
	v_or_b32_e32 v84, s26, v149
	v_sub_u32_e32 v85, v82, v84
	v_cmp_gt_u32_e32 vcc, s19, v85
	v_med3_i32 v85, v85, 0, v156
	v_lshl_add_u32 v85, v85, 2, s17
	ds_read_b32 v85, v85
	v_cmp_le_u32_e64 s[6:7], s12, v84
	s_and_b64 vcc, s[6:7], vcc
	v_max3_f32 v83, v83, v64, v65
	s_waitcnt lgkmcnt(0)
	v_fmac_f32_e32 v85, 0x3db504f3, v34
	v_cndmask_b32_e32 v34, v183, v85, vcc
	v_or_b32_e32 v85, 1, v84
	v_sub_u32_e32 v86, v82, v85
	v_cmp_le_u32_e64 s[6:7], s12, v85
	v_med3_i32 v85, v86, 0, v156
	v_lshl_add_u32 v85, v85, 2, s17
	ds_read_b32 v85, v85
	v_cmp_gt_u32_e32 vcc, s19, v86
	s_and_b64 vcc, s[6:7], vcc
	s_waitcnt lgkmcnt(0)
	v_fmac_f32_e32 v85, 0x3db504f3, v35
	v_cndmask_b32_e32 v35, v183, v85, vcc
	v_or_b32_e32 v85, 2, v84
	v_sub_u32_e32 v86, v82, v85
	v_cmp_le_u32_e64 s[6:7], s12, v85
	v_med3_i32 v85, v86, 0, v156
	v_lshl_add_u32 v85, v85, 2, s17
	ds_read_b32 v85, v85
	v_cmp_gt_u32_e32 vcc, s19, v86
	s_and_b64 vcc, s[6:7], vcc
	v_max3_f32 v83, v83, v34, v35
	s_waitcnt lgkmcnt(0)
	v_fmac_f32_e32 v85, 0x3db504f3, v36
	v_cndmask_b32_e32 v36, v183, v85, vcc
	v_or_b32_e32 v85, 3, v84
	v_sub_u32_e32 v86, v82, v85
	v_cmp_le_u32_e64 s[6:7], s12, v85
	v_med3_i32 v85, v86, 0, v156
	v_lshl_add_u32 v85, v85, 2, s17
	ds_read_b32 v85, v85
	v_cmp_gt_u32_e32 vcc, s19, v86
	s_and_b64 vcc, s[6:7], vcc
	s_waitcnt lgkmcnt(0)
	v_fmac_f32_e32 v85, 0x3db504f3, v37
	v_cndmask_b32_e32 v37, v183, v85, vcc
	v_or_b32_e32 v85, 8, v84
	v_sub_u32_e32 v86, v82, v85
	v_cmp_le_u32_e64 s[6:7], s12, v85
	v_med3_i32 v85, v86, 0, v156
	v_lshl_add_u32 v85, v85, 2, s17
	ds_read_b32 v85, v85
	v_cmp_gt_u32_e32 vcc, s19, v86
	s_and_b64 vcc, s[6:7], vcc
	v_max3_f32 v83, v83, v36, v37
	s_waitcnt lgkmcnt(0)
	v_fmac_f32_e32 v85, 0x3db504f3, v38
	v_cndmask_b32_e32 v38, v183, v85, vcc
	v_or_b32_e32 v85, 9, v84
	v_sub_u32_e32 v86, v82, v85
	v_cmp_le_u32_e64 s[6:7], s12, v85
	v_med3_i32 v85, v86, 0, v156
	v_lshl_add_u32 v85, v85, 2, s17
	ds_read_b32 v85, v85
	v_cmp_gt_u32_e32 vcc, s19, v86
	s_and_b64 vcc, s[6:7], vcc
	s_waitcnt lgkmcnt(0)
	v_fmac_f32_e32 v85, 0x3db504f3, v39
	v_cndmask_b32_e32 v39, v183, v85, vcc
	v_or_b32_e32 v85, 10, v84
	v_sub_u32_e32 v86, v82, v85
	v_cmp_le_u32_e64 s[6:7], s12, v85
	v_med3_i32 v85, v86, 0, v156
	v_lshl_add_u32 v85, v85, 2, s17
	ds_read_b32 v85, v85
	v_cmp_gt_u32_e32 vcc, s19, v86
	s_and_b64 vcc, s[6:7], vcc
	v_max3_f32 v83, v83, v38, v39
	s_waitcnt lgkmcnt(0)
	v_fmac_f32_e32 v85, 0x3db504f3, v40
	v_cndmask_b32_e32 v40, v183, v85, vcc
	v_or_b32_e32 v85, 11, v84
	v_sub_u32_e32 v86, v82, v85
	v_cmp_le_u32_e64 s[6:7], s12, v85
	v_med3_i32 v85, v86, 0, v156
	v_lshl_add_u32 v85, v85, 2, s17
	ds_read_b32 v85, v85
	v_cmp_gt_u32_e32 vcc, s19, v86
	s_and_b64 vcc, s[6:7], vcc
	s_waitcnt lgkmcnt(0)
	v_fmac_f32_e32 v85, 0x3db504f3, v41
	v_cndmask_b32_e32 v41, v183, v85, vcc
	v_or_b32_e32 v85, 16, v84
	v_sub_u32_e32 v86, v82, v85
	v_cmp_le_u32_e64 s[6:7], s12, v85
	v_med3_i32 v85, v86, 0, v156
	v_lshl_add_u32 v85, v85, 2, s17
	ds_read_b32 v85, v85
	v_cmp_gt_u32_e32 vcc, s19, v86
	s_and_b64 vcc, s[6:7], vcc
	v_max3_f32 v83, v83, v40, v41
	s_waitcnt lgkmcnt(0)
	v_fmac_f32_e32 v85, 0x3db504f3, v42
	v_cndmask_b32_e32 v42, v183, v85, vcc
	v_or_b32_e32 v85, 17, v84
	v_sub_u32_e32 v86, v82, v85
	v_cmp_le_u32_e64 s[6:7], s12, v85
	v_med3_i32 v85, v86, 0, v156
	v_lshl_add_u32 v85, v85, 2, s17
	ds_read_b32 v85, v85
	v_cmp_gt_u32_e32 vcc, s19, v86
	s_and_b64 vcc, s[6:7], vcc
	s_waitcnt lgkmcnt(0)
	v_fmac_f32_e32 v85, 0x3db504f3, v43
	v_cndmask_b32_e32 v43, v183, v85, vcc
	v_or_b32_e32 v85, 18, v84
	v_sub_u32_e32 v86, v82, v85
	v_cmp_le_u32_e64 s[6:7], s12, v85
	v_med3_i32 v85, v86, 0, v156
	v_lshl_add_u32 v85, v85, 2, s17
	ds_read_b32 v85, v85
	v_cmp_gt_u32_e32 vcc, s19, v86
	s_and_b64 vcc, s[6:7], vcc
	v_max3_f32 v83, v83, v42, v43
	s_waitcnt lgkmcnt(0)
	v_fmac_f32_e32 v85, 0x3db504f3, v44
	v_cndmask_b32_e32 v44, v183, v85, vcc
	v_or_b32_e32 v85, 19, v84
	v_sub_u32_e32 v86, v82, v85
	v_cmp_le_u32_e64 s[6:7], s12, v85
	v_med3_i32 v85, v86, 0, v156
	v_lshl_add_u32 v85, v85, 2, s17
	ds_read_b32 v85, v85
	v_cmp_gt_u32_e32 vcc, s19, v86
	s_and_b64 vcc, s[6:7], vcc
	s_waitcnt lgkmcnt(0)
	v_fmac_f32_e32 v85, 0x3db504f3, v45
	v_cndmask_b32_e32 v45, v183, v85, vcc
	v_or_b32_e32 v85, 24, v84
	v_sub_u32_e32 v86, v82, v85
	v_cmp_le_u32_e64 s[6:7], s12, v85
	v_med3_i32 v85, v86, 0, v156
	v_lshl_add_u32 v85, v85, 2, s17
	ds_read_b32 v85, v85
	v_cmp_gt_u32_e32 vcc, s19, v86
	s_and_b64 vcc, s[6:7], vcc
	v_max3_f32 v83, v83, v44, v45
	s_waitcnt lgkmcnt(0)
	v_fmac_f32_e32 v85, 0x3db504f3, v46
	v_cndmask_b32_e32 v46, v183, v85, vcc
	v_or_b32_e32 v85, 25, v84
	v_sub_u32_e32 v86, v82, v85
	v_cmp_le_u32_e64 s[6:7], s12, v85
	v_med3_i32 v85, v86, 0, v156
	v_lshl_add_u32 v85, v85, 2, s17
	ds_read_b32 v85, v85
	v_cmp_gt_u32_e32 vcc, s19, v86
	s_and_b64 vcc, s[6:7], vcc
	s_waitcnt lgkmcnt(0)
	v_fmac_f32_e32 v85, 0x3db504f3, v47
	v_cndmask_b32_e32 v47, v183, v85, vcc
	v_or_b32_e32 v85, 26, v84
	v_sub_u32_e32 v86, v82, v85
	v_cmp_le_u32_e64 s[6:7], s12, v85
	v_med3_i32 v85, v86, 0, v156
	v_lshl_add_u32 v85, v85, 2, s17
	ds_read_b32 v85, v85
	v_cmp_gt_u32_e32 vcc, s19, v86
	s_and_b64 vcc, s[6:7], vcc
	v_or_b32_e32 v84, 27, v84
	v_cmp_le_u32_e64 s[6:7], s12, v84
	s_waitcnt lgkmcnt(0)
; template <int NT>
; __device__ __forceinline__ void attn_qtile(const LAS unsigned char* lds, int ktile0, const bf16x8 (&Q)[8], int r, int kmin, int kmax, int g, float sink, bf16* orow, int lane) {
;     ...
;     for (int t = 0; t < NT; ++t)
; #pragma unroll
;         for (int i = 0; i < 16; ++i) { const int kidx = 32 * (ktile0 + t) + (i & 3) + 8 * (i >> 2) + 4 * h; const int dist = 128 + r - kidx;
;             const bool valid = (dist >= 0) && (dist <= 128) && (kidx >= kmin) && (kidx < kmax);
;             const int di = dist < 0 ? 0 : (dist > 128 ? 128 : dist);
;             float s = X[t][i] * SCALE + lut[di]; s = valid ? s : -1e30f; X[t][i] = s; mx = fmaxf(mx, s); }
	v_fmac_f32_e32 v85, 0x3db504f3, v48
	v_cndmask_b32_e32 v48, v183, v85, vcc
	v_sub_u32_e32 v85, v82, v84
	v_med3_i32 v84, v85, 0, v156
	v_lshl_add_u32 v84, v84, 2, s17
	ds_read_b32 v84, v84
	v_cmp_gt_u32_e32 vcc, s19, v85
	s_and_b64 vcc, s[6:7], vcc
	v_max3_f32 v83, v83, v46, v47
	s_waitcnt lgkmcnt(0)
	v_fmac_f32_e32 v84, 0x3db504f3, v49
	v_cndmask_b32_e32 v49, v183, v84, vcc
	v_or_b32_e32 v84, s74, v149
	v_sub_u32_e32 v85, v82, v84
	v_cmp_gt_u32_e32 vcc, s19, v85
	v_med3_i32 v85, v85, 0, v156
	v_lshl_add_u32 v85, v85, 2, s17
	ds_read_b32 v85, v85
	v_cmp_le_u32_e64 s[6:7], s12, v84
	s_and_b64 vcc, s[6:7], vcc
	v_max3_f32 v83, v83, v48, v49
	s_waitcnt lgkmcnt(0)
	v_fmac_f32_e32 v85, 0x3db504f3, v18
	v_cndmask_b32_e32 v18, v183, v85, vcc
	v_or_b32_e32 v85, 1, v84
	v_sub_u32_e32 v86, v82, v85
	v_cmp_le_u32_e64 s[6:7], s12, v85
	v_med3_i32 v85, v86, 0, v156
	v_lshl_add_u32 v85, v85, 2, s17
	ds_read_b32 v85, v85
	v_cmp_gt_u32_e32 vcc, s19, v86
	s_and_b64 vcc, s[6:7], vcc
	s_waitcnt lgkmcnt(0)
	v_fmac_f32_e32 v85, 0x3db504f3, v19
	v_cndmask_b32_e32 v19, v183, v85, vcc
	v_or_b32_e32 v85, 2, v84
	v_sub_u32_e32 v86, v82, v85
	v_cmp_le_u32_e64 s[6:7], s12, v85
	v_med3_i32 v85, v86, 0, v156
	v_lshl_add_u32 v85, v85, 2, s17
	ds_read_b32 v85, v85
	v_cmp_gt_u32_e32 vcc, s19, v86
	s_and_b64 vcc, s[6:7], vcc
	v_max3_f32 v83, v83, v18, v19
	s_waitcnt lgkmcnt(0)
	v_fmac_f32_e32 v85, 0x3db504f3, v20
	v_cndmask_b32_e32 v20, v183, v85, vcc
	v_or_b32_e32 v85, 3, v84
	v_sub_u32_e32 v86, v82, v85
	v_cmp_le_u32_e64 s[6:7], s12, v85
	v_med3_i32 v85, v86, 0, v156
	v_lshl_add_u32 v85, v85, 2, s17
	ds_read_b32 v85, v85
	v_cmp_gt_u32_e32 vcc, s19, v86
	s_and_b64 vcc, s[6:7], vcc
	s_waitcnt lgkmcnt(0)
	v_fmac_f32_e32 v85, 0x3db504f3, v21
	v_cndmask_b32_e32 v21, v183, v85, vcc
	v_or_b32_e32 v85, 8, v84
	v_sub_u32_e32 v86, v82, v85
	v_cmp_le_u32_e64 s[6:7], s12, v85
	v_med3_i32 v85, v86, 0, v156
	v_lshl_add_u32 v85, v85, 2, s17
	ds_read_b32 v85, v85
	v_cmp_gt_u32_e32 vcc, s19, v86
	s_and_b64 vcc, s[6:7], vcc
	v_max3_f32 v83, v83, v20, v21
	s_waitcnt lgkmcnt(0)
	v_fmac_f32_e32 v85, 0x3db504f3, v22
	v_cndmask_b32_e32 v22, v183, v85, vcc
	v_or_b32_e32 v85, 9, v84
	v_sub_u32_e32 v86, v82, v85
	v_cmp_le_u32_e64 s[6:7], s12, v85
	v_med3_i32 v85, v86, 0, v156
	v_lshl_add_u32 v85, v85, 2, s17
	ds_read_b32 v85, v85
	v_cmp_gt_u32_e32 vcc, s19, v86
	s_and_b64 vcc, s[6:7], vcc
	s_waitcnt lgkmcnt(0)
	v_fmac_f32_e32 v85, 0x3db504f3, v23
	v_cndmask_b32_e32 v23, v183, v85, vcc
	v_or_b32_e32 v85, 10, v84
	v_sub_u32_e32 v86, v82, v85
	v_cmp_le_u32_e64 s[6:7], s12, v85
	v_med3_i32 v85, v86, 0, v156
	v_lshl_add_u32 v85, v85, 2, s17
	ds_read_b32 v85, v85
	v_cmp_gt_u32_e32 vcc, s19, v86
	s_and_b64 vcc, s[6:7], vcc
	v_max3_f32 v83, v83, v22, v23
	s_waitcnt lgkmcnt(0)
	v_fmac_f32_e32 v85, 0x3db504f3, v24
	v_cndmask_b32_e32 v24, v183, v85, vcc
	v_or_b32_e32 v85, 11, v84
	v_sub_u32_e32 v86, v82, v85
	v_cmp_le_u32_e64 s[6:7], s12, v85
	v_med3_i32 v85, v86, 0, v156
	v_lshl_add_u32 v85, v85, 2, s17
	ds_read_b32 v85, v85
	v_cmp_gt_u32_e32 vcc, s19, v86
	s_and_b64 vcc, s[6:7], vcc
	s_waitcnt lgkmcnt(0)
	v_fmac_f32_e32 v85, 0x3db504f3, v25
	v_cndmask_b32_e32 v25, v183, v85, vcc
	v_or_b32_e32 v85, 16, v84
	v_sub_u32_e32 v86, v82, v85
	v_cmp_le_u32_e64 s[6:7], s12, v85
	v_med3_i32 v85, v86, 0, v156
	v_lshl_add_u32 v85, v85, 2, s17
	ds_read_b32 v85, v85
	v_cmp_gt_u32_e32 vcc, s19, v86
	s_and_b64 vcc, s[6:7], vcc
	v_max3_f32 v83, v83, v24, v25
	s_waitcnt lgkmcnt(0)
	v_fmac_f32_e32 v85, 0x3db504f3, v26
	v_cndmask_b32_e32 v26, v183, v85, vcc
	v_or_b32_e32 v85, 17, v84
	v_sub_u32_e32 v86, v82, v85
	v_cmp_le_u32_e64 s[6:7], s12, v85
	v_med3_i32 v85, v86, 0, v156
	v_lshl_add_u32 v85, v85, 2, s17
	ds_read_b32 v85, v85
	v_cmp_gt_u32_e32 vcc, s19, v86
	s_and_b64 vcc, s[6:7], vcc
	s_waitcnt lgkmcnt(0)
	v_fmac_f32_e32 v85, 0x3db504f3, v27
	v_cndmask_b32_e32 v27, v183, v85, vcc
	v_or_b32_e32 v85, 18, v84
	v_sub_u32_e32 v86, v82, v85
	v_cmp_le_u32_e64 s[6:7], s12, v85
	v_med3_i32 v85, v86, 0, v156
	v_lshl_add_u32 v85, v85, 2, s17
	ds_read_b32 v85, v85
	v_cmp_gt_u32_e32 vcc, s19, v86
	s_and_b64 vcc, s[6:7], vcc
	v_max3_f32 v83, v83, v26, v27
	s_waitcnt lgkmcnt(0)
	v_fmac_f32_e32 v85, 0x3db504f3, v28
	v_cndmask_b32_e32 v28, v183, v85, vcc
	v_or_b32_e32 v85, 19, v84
	v_sub_u32_e32 v86, v82, v85
	v_cmp_le_u32_e64 s[6:7], s12, v85
	v_med3_i32 v85, v86, 0, v156
	v_lshl_add_u32 v85, v85, 2, s17
	ds_read_b32 v85, v85
	v_cmp_gt_u32_e32 vcc, s19, v86
	s_and_b64 vcc, s[6:7], vcc
	s_waitcnt lgkmcnt(0)
	v_fmac_f32_e32 v85, 0x3db504f3, v29
	v_cndmask_b32_e32 v29, v183, v85, vcc
	v_or_b32_e32 v85, 24, v84
	v_sub_u32_e32 v86, v82, v85
	v_cmp_le_u32_e64 s[6:7], s12, v85
	v_med3_i32 v85, v86, 0, v156
	v_lshl_add_u32 v85, v85, 2, s17
	ds_read_b32 v85, v85
	v_cmp_gt_u32_e32 vcc, s19, v86
	s_and_b64 vcc, s[6:7], vcc
	v_max3_f32 v83, v83, v28, v29
	s_waitcnt lgkmcnt(0)
	v_fmac_f32_e32 v85, 0x3db504f3, v30
	v_cndmask_b32_e32 v30, v183, v85, vcc
	v_or_b32_e32 v85, 25, v84
	v_sub_u32_e32 v86, v82, v85
	v_cmp_le_u32_e64 s[6:7], s12, v85
	v_med3_i32 v85, v86, 0, v156
	v_lshl_add_u32 v85, v85, 2, s17
	ds_read_b32 v85, v85
	v_cmp_gt_u32_e32 vcc, s19, v86
	s_and_b64 vcc, s[6:7], vcc
	s_waitcnt lgkmcnt(0)
	v_fmac_f32_e32 v85, 0x3db504f3, v31
	v_cndmask_b32_e32 v31, v183, v85, vcc
	v_or_b32_e32 v85, 26, v84
	v_sub_u32_e32 v86, v82, v85
	v_cmp_le_u32_e64 s[6:7], s12, v85
	v_med3_i32 v85, v86, 0, v156
	v_lshl_add_u32 v85, v85, 2, s17
	ds_read_b32 v85, v85
	v_cmp_gt_u32_e32 vcc, s19, v86
	s_and_b64 vcc, s[6:7], vcc
	v_or_b32_e32 v84, 27, v84
	v_cmp_le_u32_e64 s[6:7], s12, v84
	s_waitcnt lgkmcnt(0)
; template <int NT>
; __device__ __forceinline__ void attn_qtile(const LAS unsigned char* lds, int ktile0, const bf16x8 (&Q)[8], int r, int kmin, int kmax, int g, float sink, bf16* orow, int lane) {
;     ...
;     for (int t = 0; t < NT; ++t)
; #pragma unroll
;         for (int i = 0; i < 16; ++i) { const int kidx = 32 * (ktile0 + t) + (i & 3) + 8 * (i >> 2) + 4 * h; const int dist = 128 + r - kidx;
;             const bool valid = (dist >= 0) && (dist <= 128) && (kidx >= kmin) && (kidx < kmax);
;             const int di = dist < 0 ? 0 : (dist > 128 ? 128 : dist);
;             float s = X[t][i] * SCALE + lut[di]; s = valid ? s : -1e30f; X[t][i] = s; mx = fmaxf(mx, s); }
;     mx = fmaxf(mx, __shfl_xor(mx, 32));
	v_fmac_f32_e32 v85, 0x3db504f3, v32
	v_cndmask_b32_e32 v32, v183, v85, vcc
	v_sub_u32_e32 v85, v82, v84
	v_med3_i32 v84, v85, 0, v156
	v_lshl_add_u32 v84, v84, 2, s17
	ds_read_b32 v84, v84
	v_cmp_gt_u32_e32 vcc, s19, v85
	s_and_b64 vcc, s[6:7], vcc
	v_max3_f32 v83, v83, v30, v31
	s_waitcnt lgkmcnt(0)
	v_fmac_f32_e32 v84, 0x3db504f3, v33
	v_cndmask_b32_e32 v33, v183, v84, vcc
	v_or_b32_e32 v84, s73, v149
	v_sub_u32_e32 v85, v82, v84
	v_cmp_gt_u32_e32 vcc, s19, v85
	v_med3_i32 v85, v85, 0, v156
	v_lshl_add_u32 v85, v85, 2, s17
	ds_read_b32 v85, v85
	v_max3_f32 v83, v83, v32, v33
	s_waitcnt lgkmcnt(0)
	v_fmac_f32_e32 v85, 0x3db504f3, v2
	v_cndmask_b32_e32 v2, v183, v85, vcc
	v_xad_u32 v85, v84, -1, v82
	v_cmp_gt_u32_e32 vcc, s19, v85
	v_med3_i32 v85, v85, 0, v156
	v_lshl_add_u32 v85, v85, 2, s17
	ds_read_b32 v85, v85
	s_waitcnt lgkmcnt(0)
	v_fmac_f32_e32 v85, 0x3db504f3, v3
	v_cndmask_b32_e32 v3, v183, v85, vcc
	v_or_b32_e32 v85, 2, v84
	v_sub_u32_e32 v85, v82, v85
	v_cmp_gt_u32_e32 vcc, s19, v85
	v_med3_i32 v85, v85, 0, v156
	v_lshl_add_u32 v85, v85, 2, s17
	ds_read_b32 v85, v85
	v_max3_f32 v83, v83, v2, v3
	s_waitcnt lgkmcnt(0)
	v_fmac_f32_e32 v85, 0x3db504f3, v4
	v_cndmask_b32_e32 v4, v183, v85, vcc
	v_or_b32_e32 v85, 3, v84
	v_sub_u32_e32 v85, v82, v85
	v_cmp_gt_u32_e32 vcc, s19, v85
	v_med3_i32 v85, v85, 0, v156
	v_lshl_add_u32 v85, v85, 2, s17
	ds_read_b32 v85, v85
	s_waitcnt lgkmcnt(0)
	v_fmac_f32_e32 v85, 0x3db504f3, v5
	v_cndmask_b32_e32 v5, v183, v85, vcc
	v_or_b32_e32 v85, 8, v84
	v_sub_u32_e32 v85, v82, v85
	v_cmp_gt_u32_e32 vcc, s19, v85
	v_med3_i32 v85, v85, 0, v156
	v_lshl_add_u32 v85, v85, 2, s17
	ds_read_b32 v85, v85
	v_max3_f32 v83, v83, v4, v5
	s_waitcnt lgkmcnt(0)
	v_fmac_f32_e32 v85, 0x3db504f3, v6
	v_cndmask_b32_e32 v6, v183, v85, vcc
	v_or_b32_e32 v85, 9, v84
	v_sub_u32_e32 v85, v82, v85
	v_cmp_gt_u32_e32 vcc, s19, v85
	v_med3_i32 v85, v85, 0, v156
	v_lshl_add_u32 v85, v85, 2, s17
	ds_read_b32 v85, v85
	s_waitcnt lgkmcnt(0)
	v_fmac_f32_e32 v85, 0x3db504f3, v7
	v_cndmask_b32_e32 v7, v183, v85, vcc
	v_or_b32_e32 v85, 10, v84
	v_sub_u32_e32 v85, v82, v85
	v_cmp_gt_u32_e32 vcc, s19, v85
	v_med3_i32 v85, v85, 0, v156
	v_lshl_add_u32 v85, v85, 2, s17
	ds_read_b32 v85, v85
	v_max3_f32 v83, v83, v6, v7
	s_waitcnt lgkmcnt(0)
	v_fmac_f32_e32 v85, 0x3db504f3, v8
	v_cndmask_b32_e32 v8, v183, v85, vcc
	v_or_b32_e32 v85, 11, v84
	v_sub_u32_e32 v85, v82, v85
	v_cmp_gt_u32_e32 vcc, s19, v85
	v_med3_i32 v85, v85, 0, v156
	v_lshl_add_u32 v85, v85, 2, s17
	ds_read_b32 v85, v85
	s_waitcnt lgkmcnt(0)
	v_fmac_f32_e32 v85, 0x3db504f3, v9
	v_cndmask_b32_e32 v9, v183, v85, vcc
	v_or_b32_e32 v85, 16, v84
	v_sub_u32_e32 v85, v82, v85
	v_cmp_gt_u32_e32 vcc, s19, v85
	v_med3_i32 v85, v85, 0, v156
	v_lshl_add_u32 v85, v85, 2, s17
	ds_read_b32 v85, v85
	v_max3_f32 v83, v83, v8, v9
	s_waitcnt lgkmcnt(0)
	v_fmac_f32_e32 v85, 0x3db504f3, v10
	v_cndmask_b32_e32 v10, v183, v85, vcc
	v_or_b32_e32 v85, 17, v84
	v_sub_u32_e32 v85, v82, v85
	v_cmp_gt_u32_e32 vcc, s19, v85
	v_med3_i32 v85, v85, 0, v156
	v_lshl_add_u32 v85, v85, 2, s17
	ds_read_b32 v85, v85
	s_waitcnt lgkmcnt(0)
	v_fmac_f32_e32 v85, 0x3db504f3, v11
	v_cndmask_b32_e32 v11, v183, v85, vcc
	v_or_b32_e32 v85, 18, v84
	v_sub_u32_e32 v85, v82, v85
	v_cmp_gt_u32_e32 vcc, s19, v85
	v_med3_i32 v85, v85, 0, v156
	v_lshl_add_u32 v85, v85, 2, s17
	ds_read_b32 v85, v85
	v_max3_f32 v83, v83, v10, v11
	s_waitcnt lgkmcnt(0)
	v_fmac_f32_e32 v85, 0x3db504f3, v12
	v_cndmask_b32_e32 v12, v183, v85, vcc
	v_or_b32_e32 v85, 19, v84
	v_sub_u32_e32 v85, v82, v85
	v_cmp_gt_u32_e32 vcc, s19, v85
	v_med3_i32 v85, v85, 0, v156
	v_lshl_add_u32 v85, v85, 2, s17
	ds_read_b32 v85, v85
	s_waitcnt lgkmcnt(0)
	v_fmac_f32_e32 v85, 0x3db504f3, v13
	v_cndmask_b32_e32 v13, v183, v85, vcc
	v_or_b32_e32 v85, 24, v84
	v_sub_u32_e32 v85, v82, v85
	v_cmp_gt_u32_e32 vcc, s19, v85
	v_med3_i32 v85, v85, 0, v156
	v_lshl_add_u32 v85, v85, 2, s17
	ds_read_b32 v85, v85
	v_max3_f32 v83, v83, v12, v13
	s_waitcnt lgkmcnt(0)
	v_fmac_f32_e32 v85, 0x3db504f3, v14
	v_cndmask_b32_e32 v14, v183, v85, vcc
	v_or_b32_e32 v85, 25, v84
	v_sub_u32_e32 v85, v82, v85
	v_cmp_gt_u32_e32 vcc, s19, v85
	v_med3_i32 v85, v85, 0, v156
	v_lshl_add_u32 v85, v85, 2, s17
	ds_read_b32 v85, v85
	s_waitcnt lgkmcnt(0)
	v_fmac_f32_e32 v85, 0x3db504f3, v15
	v_cndmask_b32_e32 v15, v183, v85, vcc
	v_or_b32_e32 v85, 26, v84
	v_sub_u32_e32 v85, v82, v85
	v_cmp_gt_u32_e32 vcc, s19, v85
	v_med3_i32 v85, v85, 0, v156
	v_lshl_add_u32 v85, v85, 2, s17
	ds_read_b32 v85, v85
	v_or_b32_e32 v84, 27, v84
	v_sub_u32_e32 v82, v82, v84
	v_max3_f32 v83, v83, v14, v15
	s_waitcnt lgkmcnt(0)
	v_fmac_f32_e32 v85, 0x3db504f3, v16
	v_cndmask_b32_e32 v16, v183, v85, vcc
	v_cmp_gt_u32_e32 vcc, s19, v82
	v_med3_i32 v82, v82, 0, v156
	v_lshl_add_u32 v82, v82, 2, s17
	ds_read_b32 v82, v82
	s_waitcnt lgkmcnt(0)
	v_fmac_f32_e32 v82, 0x3db504f3, v17
	v_cndmask_b32_e32 v17, v183, v82, vcc
	v_max3_f32 v82, v83, v16, v17
	ds_bpermute_b32 v83, v123, v82
	s_waitcnt lgkmcnt(0)
; template <int NT>
; __device__ __forceinline__ void attn_qtile(const LAS unsigned char* lds, int ktile0, const bf16x8 (&Q)[8], int r, int kmin, int kmax, int g, float sink, bf16* orow, int lane) {
;     ...
;     float sum = 0.f;
; #pragma unroll
;     for (int t = 0; t < NT; ++t)
; #pragma unroll
;         for (int i = 0; i < 16; ++i) { const float p = __expf(X[t][i] - mx); X[t][i] = p; sum += p; }
	v_max_f32_e32 v83, v83, v83
	v_max_f32_e32 v197, v82, v83
	v_sub_f32_e32 v71, v71, v197
	v_mul_f32_e32 v71, 0x3fb8aa3b, v71
	v_exp_f32_e32 v204, v71
	v_sub_f32_e32 v71, v72, v197
	v_mul_f32_e32 v71, 0x3fb8aa3b, v71
	v_exp_f32_e32 v205, v71
	v_sub_f32_e32 v71, v73, v197
	v_sub_f32_e32 v66, v66, v197
	v_mul_f32_e32 v71, 0x3fb8aa3b, v71
	v_mul_f32_e32 v66, 0x3fb8aa3b, v66
	v_sub_f32_e32 v67, v67, v197
	v_exp_f32_e32 v206, v71
	v_sub_f32_e32 v71, v74, v197
	v_exp_f32_e32 v66, v66
	v_mul_f32_e32 v67, 0x3fb8aa3b, v67
	v_sub_f32_e32 v68, v68, v197
	v_mul_f32_e32 v71, 0x3fb8aa3b, v71
	v_exp_f32_e32 v67, v67
	v_mul_f32_e32 v68, 0x3fb8aa3b, v68
	v_sub_f32_e32 v69, v69, v197
	v_exp_f32_e32 v207, v71
	v_sub_f32_e32 v71, v75, v197
	v_sub_f32_e32 v51, v51, v197
	v_exp_f32_e32 v68, v68
	v_mul_f32_e32 v69, 0x3fb8aa3b, v69
	v_sub_f32_e32 v70, v70, v197
	v_mul_f32_e32 v71, 0x3fb8aa3b, v71
	v_mul_f32_e32 v51, 0x3fb8aa3b, v51
	v_exp_f32_e32 v69, v69
	v_mul_f32_e32 v70, 0x3fb8aa3b, v70
	v_exp_f32_e32 v208, v71
	v_sub_f32_e32 v71, v76, v197
	v_exp_f32_e32 v216, v51
	v_sub_f32_e32 v51, v52, v197
	v_add_f32_e32 v82, 0, v66
	v_exp_f32_e32 v203, v70
	v_mul_f32_e32 v71, 0x3fb8aa3b, v71
	v_mul_f32_e32 v51, 0x3fb8aa3b, v51
	v_add_f32_e32 v82, v67, v82
	v_exp_f32_e32 v209, v71
	v_sub_f32_e32 v71, v77, v197
	v_exp_f32_e32 v217, v51
	v_sub_f32_e32 v51, v53, v197
	v_add_f32_e32 v82, v68, v82
	v_mul_f32_e32 v71, 0x3fb8aa3b, v71
	v_mul_f32_e32 v51, 0x3fb8aa3b, v51
	v_add_f32_e32 v82, v69, v82
	v_exp_f32_e32 v210, v71
	v_sub_f32_e32 v71, v78, v197
	v_exp_f32_e32 v218, v51
	v_sub_f32_e32 v51, v54, v197
	v_add_f32_e32 v70, v203, v82
	v_mul_f32_e32 v71, 0x3fb8aa3b, v71
	v_mul_f32_e32 v51, 0x3fb8aa3b, v51
	v_add_f32_e32 v70, v204, v70
	v_exp_f32_e32 v211, v71
	v_sub_f32_e32 v71, v79, v197
	v_exp_f32_e32 v219, v51
	v_sub_f32_e32 v51, v55, v197
	v_add_f32_e32 v70, v205, v70
	v_mul_f32_e32 v71, 0x3fb8aa3b, v71
	v_mul_f32_e32 v51, 0x3fb8aa3b, v51
	v_add_f32_e32 v70, v206, v70
	v_exp_f32_e32 v212, v71
	v_sub_f32_e32 v71, v80, v197
	v_exp_f32_e32 v220, v51
	v_sub_f32_e32 v51, v56, v197
	v_add_f32_e32 v70, v207, v70
	v_mul_f32_e32 v71, 0x3fb8aa3b, v71
	v_mul_f32_e32 v51, 0x3fb8aa3b, v51
	v_add_f32_e32 v70, v208, v70
	v_exp_f32_e32 v213, v71
	v_sub_f32_e32 v71, v81, v197
	v_exp_f32_e32 v221, v51
	v_sub_f32_e32 v51, v57, v197
	v_add_f32_e32 v70, v209, v70
	v_mul_f32_e32 v71, 0x3fb8aa3b, v71
	v_sub_f32_e32 v50, v50, v197
	v_mul_f32_e32 v51, 0x3fb8aa3b, v51
	v_add_f32_e32 v70, v210, v70
	v_exp_f32_e32 v214, v71
	v_mul_f32_e32 v50, 0x3fb8aa3b, v50
	v_exp_f32_e32 v222, v51
	v_sub_f32_e32 v51, v58, v197
	v_add_f32_e32 v70, v211, v70
	v_exp_f32_e32 v215, v50
	v_mul_f32_e32 v51, 0x3fb8aa3b, v51
	v_add_f32_e32 v70, v212, v70
	v_exp_f32_e32 v89, v51
	v_sub_f32_e32 v51, v59, v197
	v_sub_f32_e32 v35, v35, v197
	v_add_f32_e32 v70, v213, v70
	v_mul_f32_e32 v51, 0x3fb8aa3b, v51
	v_mul_f32_e32 v35, 0x3fb8aa3b, v35
	v_add_f32_e32 v70, v214, v70
	v_exp_f32_e32 v91, v51
	v_sub_f32_e32 v51, v60, v197
	v_exp_f32_e32 v106, v35
	v_sub_f32_e32 v35, v36, v197
	v_add_f32_e32 v50, v215, v70
	v_mul_f32_e32 v51, 0x3fb8aa3b, v51
	v_mul_f32_e32 v35, 0x3fb8aa3b, v35
	v_add_f32_e32 v50, v216, v50
	v_exp_f32_e32 v93, v51
	v_sub_f32_e32 v51, v61, v197
	v_exp_f32_e32 v109, v35
	v_sub_f32_e32 v35, v37, v197
	v_add_f32_e32 v50, v217, v50
	v_mul_f32_e32 v51, 0x3fb8aa3b, v51
	v_mul_f32_e32 v35, 0x3fb8aa3b, v35
	v_add_f32_e32 v50, v218, v50
	v_exp_f32_e32 v96, v51
	v_sub_f32_e32 v51, v62, v197
	v_exp_f32_e32 v188, v35
	v_sub_f32_e32 v35, v38, v197
	v_add_f32_e32 v50, v219, v50
	v_mul_f32_e32 v51, 0x3fb8aa3b, v51
	v_mul_f32_e32 v35, 0x3fb8aa3b, v35
	v_add_f32_e32 v50, v220, v50
	v_exp_f32_e32 v98, v51
	v_sub_f32_e32 v51, v63, v197
	v_exp_f32_e32 v191, v35
	v_sub_f32_e32 v35, v39, v197
	v_add_f32_e32 v50, v221, v50
	v_mul_f32_e32 v51, 0x3fb8aa3b, v51
	v_mul_f32_e32 v35, 0x3fb8aa3b, v35
	v_add_f32_e32 v50, v222, v50
	v_exp_f32_e32 v102, v51
	v_sub_f32_e32 v51, v64, v197
	v_exp_f32_e32 v194, v35
	v_sub_f32_e32 v35, v40, v197
	v_add_f32_e32 v50, v89, v50
	v_mul_f32_e32 v51, 0x3fb8aa3b, v51
	v_mul_f32_e32 v35, 0x3fb8aa3b, v35
	v_add_f32_e32 v50, v91, v50
	v_exp_f32_e32 v104, v51
	v_sub_f32_e32 v51, v65, v197
	v_exp_f32_e32 v196, v35
	v_sub_f32_e32 v35, v41, v197
	v_add_f32_e32 v50, v93, v50
	v_mul_f32_e32 v51, 0x3fb8aa3b, v51
	v_sub_f32_e32 v34, v34, v197
	v_mul_f32_e32 v35, 0x3fb8aa3b, v35
	v_add_f32_e32 v50, v96, v50
	v_exp_f32_e32 v108, v51
	v_mul_f32_e32 v34, 0x3fb8aa3b, v34
	v_exp_f32_e32 v199, v35
	v_sub_f32_e32 v35, v42, v197
	v_add_f32_e32 v50, v98, v50
	v_exp_f32_e32 v103, v34
	v_mul_f32_e32 v35, 0x3fb8aa3b, v35
	v_add_f32_e32 v50, v102, v50
	v_exp_f32_e32 v70, v35
	v_sub_f32_e32 v35, v43, v197
	v_sub_f32_e32 v19, v19, v197
	v_add_f32_e32 v50, v104, v50
	v_mul_f32_e32 v35, 0x3fb8aa3b, v35
	v_mul_f32_e32 v19, 0x3fb8aa3b, v19
	v_add_f32_e32 v50, v108, v50
	v_exp_f32_e32 v71, v35
	v_sub_f32_e32 v35, v44, v197
	v_exp_f32_e32 v78, v19
	v_sub_f32_e32 v19, v20, v197
	v_add_f32_e32 v34, v103, v50
	v_mul_f32_e32 v35, 0x3fb8aa3b, v35
	v_mul_f32_e32 v19, 0x3fb8aa3b, v19
	v_add_f32_e32 v34, v106, v34
	v_exp_f32_e32 v72, v35
	v_sub_f32_e32 v35, v45, v197
	v_exp_f32_e32 v80, v19
	v_sub_f32_e32 v19, v21, v197
	v_add_f32_e32 v34, v109, v34
	v_mul_f32_e32 v35, 0x3fb8aa3b, v35
	v_mul_f32_e32 v19, 0x3fb8aa3b, v19
	v_add_f32_e32 v34, v188, v34
	v_exp_f32_e32 v73, v35
	v_sub_f32_e32 v35, v46, v197
	v_exp_f32_e32 v81, v19
	v_sub_f32_e32 v19, v22, v197
	v_add_f32_e32 v34, v191, v34
	v_mul_f32_e32 v35, 0x3fb8aa3b, v35
	v_mul_f32_e32 v19, 0x3fb8aa3b, v19
	v_add_f32_e32 v34, v194, v34
	v_exp_f32_e32 v74, v35
	v_sub_f32_e32 v35, v47, v197
; __device__ __forceinline__ unsigned cvt_pk_bf16(float lo, float hi) { unsigned r; asm volatile("v_cvt_pk_bf16_f32 %0, %1, %2" : "=v"(r) : "v"(lo), "v"(hi)); return r; }
; #define LAS __attribute__((address_space(3)))
; template <int NT>
; __device__ __forceinline__ void attn_qtile(const LAS unsigned char* lds, int ktile0, const bf16x8 (&Q)[8], int r, int kmin, int kmax, int g, float sink, bf16* orow, int lane) {
;     ...
;     float sum = 0.f;
; #pragma unroll
;     for (int t = 0; t < NT; ++t)
; #pragma unroll
;         for (int i = 0; i < 16; ++i) { const float p = __expf(X[t][i] - mx); X[t][i] = p; sum += p; }
;     sum += __shfl_xor(sum, 32);
;     const float inv = 1.0f / (sum + __expf(sink - mx));
;     f32x16 O[4];
; #pragma unroll
;     for (int dt = 0; dt < 4; ++dt)
; #pragma unroll
;         for (int i = 0; i < 16; ++i) O[dt][i] = 0.f;
; #pragma unroll
;     for (int t = 0; t < NT; ++t)
; #pragma unroll
;         for (int s = 0; s < 2; ++s) {
;             v4u pw; pw.x = pg8::cvt_pk_bf16(X[t][8 * s + 0], X[t][8 * s + 1]); pw.y = pg8::cvt_pk_bf16(X[t][8 * s + 2], X[t][8 * s + 3]);
;             pw.z = pg8::cvt_pk_bf16(X[t][8 * s + 4], X[t][8 * s + 5]); pw.w = pg8::cvt_pk_bf16(X[t][8 * s + 6], X[t][8 * s + 7]);
;             const bf16x8 pf = __builtin_bit_cast(bf16x8, pw);
; #pragma unroll
;             for (int dt = 0; dt < 4; ++dt) { const bf16x8 vf = *(const LAS bf16x8*)(lds + V_OFF + (32 * dt + c) * VROW + (32 * (ktile0 + t) + 16 * s + 8 * h) * 2);
;                 O[dt] = __builtin_amdgcn_mfma_f32_32x32x16_bf16(vf, pf, O[dt], 0, 0, 0); }
;         }
	v_exp_f32_e32 v82, v19
	v_sub_f32_e32 v19, v23, v197
	v_add_f32_e32 v34, v196, v34
	v_mul_f32_e32 v35, 0x3fb8aa3b, v35
	v_mul_f32_e32 v19, 0x3fb8aa3b, v19
	v_add_f32_e32 v34, v199, v34
	v_exp_f32_e32 v75, v35
	v_sub_f32_e32 v35, v48, v197
	v_exp_f32_e32 v83, v19
	v_sub_f32_e32 v19, v24, v197
	v_add_f32_e32 v34, v70, v34
	v_mul_f32_e32 v35, 0x3fb8aa3b, v35
	v_mul_f32_e32 v19, 0x3fb8aa3b, v19
	v_add_f32_e32 v34, v71, v34
	v_exp_f32_e32 v77, v35
	v_sub_f32_e32 v35, v49, v197
	v_exp_f32_e32 v85, v19
	v_sub_f32_e32 v19, v25, v197
	v_add_f32_e32 v34, v72, v34
	v_mul_f32_e32 v35, 0x3fb8aa3b, v35
	v_sub_f32_e32 v18, v18, v197
	v_mul_f32_e32 v19, 0x3fb8aa3b, v19
	v_add_f32_e32 v34, v73, v34
	v_exp_f32_e32 v79, v35
	v_mul_f32_e32 v18, 0x3fb8aa3b, v18
	v_exp_f32_e32 v87, v19
	v_sub_f32_e32 v19, v26, v197
	v_add_f32_e32 v34, v74, v34
	v_exp_f32_e32 v76, v18
	v_mul_f32_e32 v19, 0x3fb8aa3b, v19
	v_add_f32_e32 v34, v75, v34
	v_exp_f32_e32 v84, v19
	v_sub_f32_e32 v19, v27, v197
	v_sub_f32_e32 v3, v3, v197
	v_add_f32_e32 v34, v77, v34
	v_mul_f32_e32 v19, 0x3fb8aa3b, v19
	v_mul_f32_e32 v3, 0x3fb8aa3b, v3
	v_add_f32_e32 v34, v79, v34
	v_exp_f32_e32 v86, v19
	v_sub_f32_e32 v19, v28, v197
	v_exp_f32_e32 v99, v3
	v_sub_f32_e32 v3, v4, v197
	v_add_f32_e32 v18, v76, v34
	v_mul_f32_e32 v19, 0x3fb8aa3b, v19
	v_mul_f32_e32 v3, 0x3fb8aa3b, v3
	v_add_f32_e32 v18, v78, v18
	v_exp_f32_e32 v88, v19
	v_sub_f32_e32 v19, v29, v197
	v_exp_f32_e32 v101, v3
	v_sub_f32_e32 v3, v5, v197
	v_add_f32_e32 v18, v80, v18
	v_mul_f32_e32 v19, 0x3fb8aa3b, v19
	v_mul_f32_e32 v3, 0x3fb8aa3b, v3
	v_add_f32_e32 v18, v81, v18
	v_exp_f32_e32 v90, v19
	v_sub_f32_e32 v19, v30, v197
	v_exp_f32_e32 v105, v3
	v_sub_f32_e32 v3, v6, v197
	v_add_f32_e32 v18, v82, v18
	v_mul_f32_e32 v19, 0x3fb8aa3b, v19
	v_mul_f32_e32 v3, 0x3fb8aa3b, v3
	v_add_f32_e32 v18, v83, v18
	v_exp_f32_e32 v92, v19
	v_sub_f32_e32 v19, v31, v197
	v_exp_f32_e32 v107, v3
	v_sub_f32_e32 v3, v7, v197
	v_add_f32_e32 v18, v85, v18
	v_mul_f32_e32 v19, 0x3fb8aa3b, v19
	v_mul_f32_e32 v3, 0x3fb8aa3b, v3
	v_add_f32_e32 v18, v87, v18
	v_exp_f32_e32 v94, v19
	v_sub_f32_e32 v19, v32, v197
	v_exp_f32_e32 v110, v3
	v_sub_f32_e32 v3, v8, v197
	v_add_f32_e32 v18, v84, v18
	v_mul_f32_e32 v19, 0x3fb8aa3b, v19
	v_mul_f32_e32 v3, 0x3fb8aa3b, v3
	v_add_f32_e32 v18, v86, v18
	v_exp_f32_e32 v97, v19
	v_sub_f32_e32 v19, v33, v197
	v_exp_f32_e32 v189, v3
	v_sub_f32_e32 v3, v9, v197
	v_add_f32_e32 v18, v88, v18
	v_mul_f32_e32 v19, 0x3fb8aa3b, v19
	v_sub_f32_e32 v2, v2, v197
	v_mul_f32_e32 v3, 0x3fb8aa3b, v3
	v_add_f32_e32 v18, v90, v18
	v_exp_f32_e32 v100, v19
	v_mul_f32_e32 v2, 0x3fb8aa3b, v2
	v_exp_f32_e32 v192, v3
	v_sub_f32_e32 v3, v10, v197
	v_add_f32_e32 v18, v92, v18
	v_exp_f32_e32 v95, v2
	v_mul_f32_e32 v3, 0x3fb8aa3b, v3
	v_add_f32_e32 v18, v94, v18
	v_exp_f32_e32 v187, v3
	v_sub_f32_e32 v3, v11, v197
	v_add_f32_e32 v18, v97, v18
	v_mul_f32_e32 v3, 0x3fb8aa3b, v3
	v_add_f32_e32 v18, v100, v18
	v_exp_f32_e32 v190, v3
	v_sub_f32_e32 v3, v12, v197
	v_add_f32_e32 v2, v95, v18
	v_mul_f32_e32 v3, 0x3fb8aa3b, v3
	v_add_f32_e32 v2, v99, v2
	v_exp_f32_e32 v193, v3
	v_sub_f32_e32 v3, v13, v197
	v_add_f32_e32 v2, v101, v2
	v_mul_f32_e32 v3, 0x3fb8aa3b, v3
	v_add_f32_e32 v2, v105, v2
	v_exp_f32_e32 v195, v3
	v_sub_f32_e32 v3, v14, v197
	v_add_f32_e32 v2, v107, v2
	v_mul_f32_e32 v3, 0x3fb8aa3b, v3
	v_add_f32_e32 v2, v110, v2
	v_exp_f32_e32 v198, v3
	v_sub_f32_e32 v3, v15, v197
	v_add_f32_e32 v2, v189, v2
	v_mul_f32_e32 v3, 0x3fb8aa3b, v3
	v_add_f32_e32 v2, v192, v2
	v_exp_f32_e32 v200, v3
	v_sub_f32_e32 v3, v16, v197
	v_add_f32_e32 v2, v187, v2
	v_mul_f32_e32 v3, 0x3fb8aa3b, v3
	v_add_f32_e32 v2, v190, v2
	v_exp_f32_e32 v201, v3
	v_sub_f32_e32 v3, v17, v197
	v_add_f32_e32 v2, v193, v2
	v_mul_f32_e32 v3, 0x3fb8aa3b, v3
	v_add_f32_e32 v2, v195, v2
	v_exp_f32_e32 v202, v3
	v_add_f32_e32 v2, v198, v2
	v_add_f32_e32 v2, v200, v2
	v_add_f32_e32 v2, v201, v2
	v_add_f32_e32 v2, v202, v2
	ds_bpermute_b32 v3, v123, v2
	s_waitcnt lgkmcnt(0)
	v_add_f32_e32 v2, v2, v3
	v_sub_f32_e32 v3, v185, v197
	v_mul_f32_e32 v3, 0x3fb8aa3b, v3
	v_exp_f32_e32 v3, v3
	s_nop 0
	v_add_f32_e32 v197, v3, v2
	v_cvt_pk_bf16_f32 v2, v66, v67
	v_cvt_pk_bf16_f32 v3, v68, v69
	v_cvt_pk_bf16_f32 v4, v203, v204
	v_lshl_add_u32 v203, s34, 6, v172
	v_cvt_pk_bf16_f32 v5, v205, v206
	ds_read_b128 v[6:9], v203
	s_waitcnt lgkmcnt(0)
	v_mfma_f32_32x32x16_bf16 v[50:65], v[6:9], v[2:5], 0
	ds_read_b128 v[6:9], v203 offset:16896
	s_waitcnt lgkmcnt(0)
	v_mfma_f32_32x32x16_bf16 v[34:49], v[6:9], v[2:5], 0
	ds_read_b128 v[6:9], v203 offset:33792
	s_waitcnt lgkmcnt(0)
	v_mfma_f32_32x32x16_bf16 v[18:33], v[6:9], v[2:5], 0
	ds_read_b128 v[6:9], v203 offset:50688
	v_cvt_pk_bf16_f32 v66, v207, v208
	v_cvt_pk_bf16_f32 v67, v209, v210
	v_cvt_pk_bf16_f32 v68, v211, v212
	v_cvt_pk_bf16_f32 v69, v213, v214
	ds_read_b128 v[204:207], v203 offset:32
	s_waitcnt lgkmcnt(0)
	v_mfma_f32_32x32x16_bf16 v[50:65], v[204:207], v[66:69], v[50:65]
	ds_read_b128 v[204:207], v203 offset:16928
	s_waitcnt lgkmcnt(0)
	v_mfma_f32_32x32x16_bf16 v[34:49], v[204:207], v[66:69], v[34:49]
	ds_read_b128 v[204:207], v203 offset:33824
	s_waitcnt lgkmcnt(0)
	v_mfma_f32_32x32x16_bf16 v[18:33], v[204:207], v[66:69], v[18:33]
	ds_read_b128 v[204:207], v203 offset:50720
	v_lshl_add_u32 v203, s13, 6, v172
	v_mfma_f32_32x32x16_bf16 v[2:17], v[6:9], v[2:5], 0
	s_waitcnt lgkmcnt(0)
	v_mfma_f32_32x32x16_bf16 v[2:17], v[204:207], v[66:69], v[2:17]
	v_cvt_pk_bf16_f32 v66, v215, v216
	v_cvt_pk_bf16_f32 v67, v217, v218
	v_cvt_pk_bf16_f32 v68, v219, v220
	v_cvt_pk_bf16_f32 v69, v221, v222
	ds_read_b128 v[204:207], v203
	ds_read_b128 v[232:235], v203 offset:16896
	s_waitcnt lgkmcnt(1)
; __device__ __forceinline__ unsigned cvt_pk_bf16(float lo, float hi) { unsigned r; asm volatile("v_cvt_pk_bf16_f32 %0, %1, %2" : "=v"(r) : "v"(lo), "v"(hi)); return r; }
; #define LAS __attribute__((address_space(3)))
; template <int NT>
; __device__ __forceinline__ void attn_qtile(const LAS unsigned char* lds, int ktile0, const bf16x8 (&Q)[8], int r, int kmin, int kmax, int g, float sink, bf16* orow, int lane) {
;     ...
;     for (int t = 0; t < NT; ++t)
; #pragma unroll
;         for (int s = 0; s < 2; ++s) {
;             v4u pw; pw.x = pg8::cvt_pk_bf16(X[t][8 * s + 0], X[t][8 * s + 1]); pw.y = pg8::cvt_pk_bf16(X[t][8 * s + 2], X[t][8 * s + 3]);
;             pw.z = pg8::cvt_pk_bf16(X[t][8 * s + 4], X[t][8 * s + 5]); pw.w = pg8::cvt_pk_bf16(X[t][8 * s + 6], X[t][8 * s + 7]);
;             const bf16x8 pf = __builtin_bit_cast(bf16x8, pw);
; #pragma unroll
;             for (int dt = 0; dt < 4; ++dt) { const bf16x8 vf = *(const LAS bf16x8*)(lds + V_OFF + (32 * dt + c) * VROW + (32 * (ktile0 + t) + 16 * s + 8 * h) * 2);
;                 O[dt] = __builtin_amdgcn_mfma_f32_32x32x16_bf16(vf, pf, O[dt], 0, 0, 0); }
;         }
	v_mfma_f32_32x32x16_bf16 v[50:65], v[204:207], v[66:69], v[50:65]
	ds_read_b128 v[204:207], v203 offset:33792
	s_waitcnt lgkmcnt(1)
	v_mfma_f32_32x32x16_bf16 v[34:49], v[232:235], v[66:69], v[34:49]
	ds_read_b128 v[232:235], v203 offset:50688
	s_waitcnt lgkmcnt(1)
	v_mfma_f32_32x32x16_bf16 v[18:33], v[204:207], v[66:69], v[18:33]
	s_waitcnt lgkmcnt(0)
	v_mfma_f32_32x32x16_bf16 v[2:17], v[232:235], v[66:69], v[2:17]
	v_cvt_pk_bf16_f32 v66, v89, v91
	v_cvt_pk_bf16_f32 v67, v93, v96
	v_cvt_pk_bf16_f32 v68, v98, v102
	v_cvt_pk_bf16_f32 v69, v104, v108
	ds_read_b128 v[204:207], v203 offset:32
	v_lshl_add_u32 v89, s8, 6, v172
	s_waitcnt lgkmcnt(0)
	v_mfma_f32_32x32x16_bf16 v[50:65], v[204:207], v[66:69], v[50:65]
	ds_read_b128 v[204:207], v203 offset:16928
	s_waitcnt lgkmcnt(0)
	v_mfma_f32_32x32x16_bf16 v[34:49], v[204:207], v[66:69], v[34:49]
	ds_read_b128 v[204:207], v203 offset:33824
	s_waitcnt lgkmcnt(0)
	v_mfma_f32_32x32x16_bf16 v[18:33], v[204:207], v[66:69], v[18:33]
	ds_read_b128 v[204:207], v203 offset:50720
	s_waitcnt lgkmcnt(0)
	v_mfma_f32_32x32x16_bf16 v[2:17], v[204:207], v[66:69], v[2:17]
	v_cvt_pk_bf16_f32 v66, v103, v106
	v_cvt_pk_bf16_f32 v67, v109, v188
	v_cvt_pk_bf16_f32 v68, v191, v194
	v_cvt_pk_bf16_f32 v69, v196, v199
	ds_read_b128 v[204:207], v89
	ds_read_b128 v[232:235], v89 offset:16896
	s_waitcnt lgkmcnt(1)
	v_mfma_f32_32x32x16_bf16 v[50:65], v[204:207], v[66:69], v[50:65]
	ds_read_b128 v[204:207], v89 offset:33792
	s_waitcnt lgkmcnt(1)
	v_mfma_f32_32x32x16_bf16 v[34:49], v[232:235], v[66:69], v[34:49]
	ds_read_b128 v[232:235], v89 offset:50688
	s_waitcnt lgkmcnt(1)
	v_mfma_f32_32x32x16_bf16 v[18:33], v[204:207], v[66:69], v[18:33]
	s_waitcnt lgkmcnt(0)
	v_mfma_f32_32x32x16_bf16 v[2:17], v[232:235], v[66:69], v[2:17]
	v_cvt_pk_bf16_f32 v66, v70, v71
	v_cvt_pk_bf16_f32 v67, v72, v73
	v_cvt_pk_bf16_f32 v68, v74, v75
	v_cvt_pk_bf16_f32 v69, v77, v79
	ds_read_b128 v[70:73], v89 offset:32
	v_lshl_add_u32 v74, s1, 6, v172
	s_waitcnt lgkmcnt(0)
	v_mfma_f32_32x32x16_bf16 v[50:65], v[70:73], v[66:69], v[50:65]
	ds_read_b128 v[70:73], v89 offset:16928
	s_waitcnt lgkmcnt(0)
	v_mfma_f32_32x32x16_bf16 v[34:49], v[70:73], v[66:69], v[34:49]
	ds_read_b128 v[70:73], v89 offset:33824
	s_waitcnt lgkmcnt(0)
	v_mfma_f32_32x32x16_bf16 v[18:33], v[70:73], v[66:69], v[18:33]
	ds_read_b128 v[70:73], v89 offset:50720
	s_waitcnt lgkmcnt(0)
	v_mfma_f32_32x32x16_bf16 v[2:17], v[70:73], v[66:69], v[2:17]
	v_cvt_pk_bf16_f32 v66, v76, v78
	v_cvt_pk_bf16_f32 v67, v80, v81
	v_cvt_pk_bf16_f32 v68, v82, v83
	v_cvt_pk_bf16_f32 v69, v85, v87
	ds_read_b128 v[70:73], v74
	ds_read_b128 v[232:235], v74 offset:16896
	s_waitcnt lgkmcnt(1)
	v_mfma_f32_32x32x16_bf16 v[50:65], v[70:73], v[66:69], v[50:65]
	ds_read_b128 v[70:73], v74 offset:33792
	s_waitcnt lgkmcnt(1)
	v_mfma_f32_32x32x16_bf16 v[34:49], v[232:235], v[66:69], v[34:49]
	ds_read_b128 v[232:235], v74 offset:50688
	s_waitcnt lgkmcnt(1)
	v_mfma_f32_32x32x16_bf16 v[18:33], v[70:73], v[66:69], v[18:33]
	s_waitcnt lgkmcnt(0)
	v_mfma_f32_32x32x16_bf16 v[2:17], v[232:235], v[66:69], v[2:17]
	v_cvt_pk_bf16_f32 v66, v84, v86
	v_cvt_pk_bf16_f32 v67, v88, v90
	v_cvt_pk_bf16_f32 v68, v92, v94
	v_cvt_pk_bf16_f32 v69, v97, v100
	ds_read_b128 v[70:73], v74 offset:32
	s_waitcnt lgkmcnt(0)
	v_mfma_f32_32x32x16_bf16 v[50:65], v[70:73], v[66:69], v[50:65]
	ds_read_b128 v[70:73], v74 offset:16928
	s_waitcnt lgkmcnt(0)
	v_mfma_f32_32x32x16_bf16 v[34:49], v[70:73], v[66:69], v[34:49]
	ds_read_b128 v[70:73], v74 offset:33824
	s_waitcnt lgkmcnt(0)
	v_mfma_f32_32x32x16_bf16 v[18:33], v[70:73], v[66:69], v[18:33]
	ds_read_b128 v[70:73], v74 offset:50720
	v_lshl_add_u32 v74, s0, 6, v172
	s_waitcnt lgkmcnt(0)
	v_mfma_f32_32x32x16_bf16 v[2:17], v[70:73], v[66:69], v[2:17]
	v_cvt_pk_bf16_f32 v66, v95, v99
	v_cvt_pk_bf16_f32 v67, v101, v105
	v_cvt_pk_bf16_f32 v68, v107, v110
	v_cvt_pk_bf16_f32 v69, v189, v192
	ds_read_b128 v[70:73], v74
	v_lshlrev_b32_e32 v110, 13, v186
	s_waitcnt lgkmcnt(0)
	v_mfma_f32_32x32x16_bf16 v[50:65], v[70:73], v[66:69], v[50:65]
	ds_read_b128 v[70:73], v74 offset:16896
	s_waitcnt lgkmcnt(0)
	v_mfma_f32_32x32x16_bf16 v[34:49], v[70:73], v[66:69], v[34:49]
	ds_read_b128 v[70:73], v74 offset:33792
	s_waitcnt lgkmcnt(0)
	v_mfma_f32_32x32x16_bf16 v[18:33], v[70:73], v[66:69], v[18:33]
	ds_read_b128 v[70:73], v74 offset:50688
	s_waitcnt lgkmcnt(0)
	v_mfma_f32_32x32x16_bf16 v[2:17], v[70:73], v[66:69], v[2:17]
	v_cvt_pk_bf16_f32 v66, v187, v190
	v_cvt_pk_bf16_f32 v67, v193, v195
	v_cvt_pk_bf16_f32 v68, v198, v200
	v_cvt_pk_bf16_f32 v69, v201, v202
	ds_read_b128 v[70:73], v74 offset:32
	ds_read_b128 v[232:235], v74 offset:16928
	s_waitcnt lgkmcnt(1)
	v_mfma_f32_32x32x16_bf16 v[50:65], v[70:73], v[66:69], v[50:65]
	ds_read_b128 v[70:73], v74 offset:33824
	s_waitcnt lgkmcnt(1)
	v_mfma_f32_32x32x16_bf16 v[34:49], v[232:235], v[66:69], v[34:49]
	ds_read_b128 v[232:235], v74 offset:50720
	s_waitcnt lgkmcnt(1)
	v_mfma_f32_32x32x16_bf16 v[18:33], v[70:73], v[66:69], v[18:33]
	s_waitcnt lgkmcnt(0)
; __device__ __forceinline__ unsigned cvt_pk_bf16(float lo, float hi) { unsigned r; asm volatile("v_cvt_pk_bf16_f32 %0, %1, %2" : "=v"(r) : "v"(lo), "v"(hi)); return r; }
; #define GAS __attribute__((address_space(1)))
; #define LAS __attribute__((address_space(3)))
; __device__ __forceinline__ unsigned pk2(float lo, float hi) { return f2bf(lo) | (f2bf(hi) << 16); }
; template <int NT>
; __device__ __forceinline__ void attn_qtile(const LAS unsigned char* lds, int ktile0, const bf16x8 (&Q)[8], int r, int kmin, int kmax, int g, float sink, bf16* orow, int lane) {
;     ...
;     const float inv = 1.0f / (sum + __expf(sink - mx));
;     f32x16 O[4];
; #pragma unroll
;     for (int dt = 0; dt < 4; ++dt)
; #pragma unroll
;         for (int i = 0; i < 16; ++i) O[dt][i] = 0.f;
; #pragma unroll
;     for (int t = 0; t < NT; ++t)
; #pragma unroll
;         for (int s = 0; s < 2; ++s) {
;             v4u pw; pw.x = pg8::cvt_pk_bf16(X[t][8 * s + 0], X[t][8 * s + 1]); pw.y = pg8::cvt_pk_bf16(X[t][8 * s + 2], X[t][8 * s + 3]);
;             pw.z = pg8::cvt_pk_bf16(X[t][8 * s + 4], X[t][8 * s + 5]); pw.w = pg8::cvt_pk_bf16(X[t][8 * s + 6], X[t][8 * s + 7]);
;             const bf16x8 pf = __builtin_bit_cast(bf16x8, pw);
; #pragma unroll
;             for (int dt = 0; dt < 4; ++dt) { const bf16x8 vf = *(const LAS bf16x8*)(lds + V_OFF + (32 * dt + c) * VROW + (32 * (ktile0 + t) + 16 * s + 8 * h) * 2);
;                 O[dt] = __builtin_amdgcn_mfma_f32_32x32x16_bf16(vf, pf, O[dt], 0, 0, 0); }
;         }
; #pragma unroll
;     for (int dt = 0; dt < 4; ++dt)
; #pragma unroll
;         for (int i = 0; i < 4; ++i) { v2u w; w.x = pk2(O[dt][4 * i + 0] * inv, O[dt][4 * i + 1] * inv); w.y = pk2(O[dt][4 * i + 2] * inv, O[dt][4 * i + 3] * inv);
;             *(GAS v2u*)(orow + 32 * dt + 8 * i + 4 * h) = w; }
	v_mfma_f32_32x32x16_bf16 v[2:17], v[232:235], v[66:69], v[2:17]
	v_div_scale_f32 v66, s[0:1], v197, v197, 1.0
	v_rcp_f32_e32 v67, v66
	s_nop 0
	v_mov_b32_e32 v71, v52
	v_mov_b32_e32 v52, v51
	s_mov_b32 s0, 1
	v_fma_f32 v68, -v66, v67, 1.0
	v_fmac_f32_e32 v67, v68, v67
	v_div_scale_f32 v68, vcc, 1.0, v197, 1.0
	v_mul_f32_e32 v69, v68, v67
	v_fma_f32 v70, -v66, v69, v68
	v_fmac_f32_e32 v69, v70, v67
	v_fma_f32 v66, -v66, v69, v68
	v_div_fmas_f32 v66, v66, v67, v69
	v_div_fixup_f32 v68, v66, v197, 1.0
	v_mov_b32_e32 v70, v50
	v_pk_mul_f32 v[70:71], v[68:69], v[70:71] op_sel_hi:[0,1]
	v_pk_mul_f32 v[50:51], v[68:69], v[52:53] op_sel_hi:[0,1]
	v_and_b32_sdwa v53, v70, v184 dst_sel:DWORD dst_unused:UNUSED_PAD src0_sel:WORD_1 src1_sel:DWORD
	v_add3_u32 v53, v70, v53, s54
	v_and_b32_sdwa v69, v51, v184 dst_sel:DWORD dst_unused:UNUSED_PAD src0_sel:WORD_1 src1_sel:DWORD
	v_and_b32_sdwa v70, v50, v184 dst_sel:DWORD dst_unused:UNUSED_PAD src0_sel:WORD_1 src1_sel:DWORD
	v_and_b32_sdwa v52, v71, v184 dst_sel:DWORD dst_unused:UNUSED_PAD src0_sel:WORD_1 src1_sel:DWORD
	v_add3_u32 v51, v51, v69, s54
	v_add3_u32 v50, v50, v70, s54
	v_add3_u32 v52, v71, v52, s54
	v_and_b32_e32 v51, 0xffff0000, v51
	v_and_b32_e32 v50, 0xffff0000, v50
	v_lshl_add_u64 v[66:67], v[146:147], 0, v[110:111]
	v_or_b32_sdwa v51, v51, v52 dst_sel:DWORD dst_unused:UNUSED_PAD src0_sel:DWORD src1_sel:WORD_1
	v_or_b32_sdwa v50, v50, v53 dst_sel:DWORD dst_unused:UNUSED_PAD src0_sel:DWORD src1_sel:WORD_1
	global_store_dwordx2 v[66:67], v[50:51], off
	v_mov_b32_e32 v50, v54
	v_mov_b32_e32 v51, v56
	v_pk_mul_f32 v[50:51], v[68:69], v[50:51] op_sel_hi:[0,1]
	v_mov_b32_e32 v56, v55
	v_pk_mul_f32 v[52:53], v[68:69], v[56:57] op_sel_hi:[0,1]
	v_and_b32_sdwa v54, v51, v184 dst_sel:DWORD dst_unused:UNUSED_PAD src0_sel:WORD_1 src1_sel:DWORD
	v_and_b32_sdwa v55, v50, v184 dst_sel:DWORD dst_unused:UNUSED_PAD src0_sel:WORD_1 src1_sel:DWORD
	v_add3_u32 v50, v50, v55, s54
	v_add3_u32 v51, v51, v54, s54
	v_and_b32_sdwa v54, v53, v184 dst_sel:DWORD dst_unused:UNUSED_PAD src0_sel:WORD_1 src1_sel:DWORD
	v_and_b32_sdwa v55, v52, v184 dst_sel:DWORD dst_unused:UNUSED_PAD src0_sel:WORD_1 src1_sel:DWORD
	v_add3_u32 v53, v53, v54, s54
	v_add3_u32 v52, v52, v55, s54
	v_and_b32_e32 v53, 0xffff0000, v53
	v_and_b32_e32 v52, 0xffff0000, v52
	v_or_b32_sdwa v51, v53, v51 dst_sel:DWORD dst_unused:UNUSED_PAD src0_sel:DWORD src1_sel:WORD_1
	v_or_b32_sdwa v50, v52, v50 dst_sel:DWORD dst_unused:UNUSED_PAD src0_sel:DWORD src1_sel:WORD_1
	global_store_dwordx2 v[66:67], v[50:51], off offset:16
	v_mov_b32_e32 v50, v58
	v_mov_b32_e32 v51, v60
	v_pk_mul_f32 v[50:51], v[68:69], v[50:51] op_sel_hi:[0,1]
	v_mov_b32_e32 v60, v59
	v_pk_mul_f32 v[52:53], v[68:69], v[60:61] op_sel_hi:[0,1]
	v_and_b32_sdwa v54, v51, v184 dst_sel:DWORD dst_unused:UNUSED_PAD src0_sel:WORD_1 src1_sel:DWORD
	v_and_b32_sdwa v55, v50, v184 dst_sel:DWORD dst_unused:UNUSED_PAD src0_sel:WORD_1 src1_sel:DWORD
	v_add3_u32 v50, v50, v55, s54
	v_add3_u32 v51, v51, v54, s54
	v_and_b32_sdwa v54, v53, v184 dst_sel:DWORD dst_unused:UNUSED_PAD src0_sel:WORD_1 src1_sel:DWORD
	v_and_b32_sdwa v55, v52, v184 dst_sel:DWORD dst_unused:UNUSED_PAD src0_sel:WORD_1 src1_sel:DWORD
	v_add3_u32 v53, v53, v54, s54
	v_add3_u32 v52, v52, v55, s54
	v_and_b32_e32 v53, 0xffff0000, v53
	v_and_b32_e32 v52, 0xffff0000, v52
	v_or_b32_sdwa v51, v53, v51 dst_sel:DWORD dst_unused:UNUSED_PAD src0_sel:DWORD src1_sel:WORD_1
	v_or_b32_sdwa v50, v52, v50 dst_sel:DWORD dst_unused:UNUSED_PAD src0_sel:DWORD src1_sel:WORD_1
	global_store_dwordx2 v[66:67], v[50:51], off offset:32
	v_mov_b32_e32 v50, v62
	v_mov_b32_e32 v51, v64
	v_pk_mul_f32 v[50:51], v[68:69], v[50:51] op_sel_hi:[0,1]
	v_mov_b32_e32 v64, v63
	v_pk_mul_f32 v[52:53], v[68:69], v[64:65] op_sel_hi:[0,1]
	v_and_b32_sdwa v54, v51, v184 dst_sel:DWORD dst_unused:UNUSED_PAD src0_sel:WORD_1 src1_sel:DWORD
	v_and_b32_sdwa v55, v50, v184 dst_sel:DWORD dst_unused:UNUSED_PAD src0_sel:WORD_1 src1_sel:DWORD
	v_add3_u32 v50, v50, v55, s54
	v_add3_u32 v51, v51, v54, s54
	v_and_b32_sdwa v54, v53, v184 dst_sel:DWORD dst_unused:UNUSED_PAD src0_sel:WORD_1 src1_sel:DWORD
	v_and_b32_sdwa v55, v52, v184 dst_sel:DWORD dst_unused:UNUSED_PAD src0_sel:WORD_1 src1_sel:DWORD
	v_add3_u32 v53, v53, v54, s54
	v_add3_u32 v52, v52, v55, s54
	v_and_b32_e32 v53, 0xffff0000, v53
	v_and_b32_e32 v52, 0xffff0000, v52
	v_or_b32_sdwa v51, v53, v51 dst_sel:DWORD dst_unused:UNUSED_PAD src0_sel:DWORD src1_sel:WORD_1
	v_or_b32_sdwa v50, v52, v50 dst_sel:DWORD dst_unused:UNUSED_PAD src0_sel:DWORD src1_sel:WORD_1
	global_store_dwordx2 v[66:67], v[50:51], off offset:48
	v_mov_b32_e32 v50, v34
	v_mov_b32_e32 v51, v36
	v_pk_mul_f32 v[50:51], v[68:69], v[50:51] op_sel_hi:[0,1]
	v_mov_b32_e32 v36, v35
	v_pk_mul_f32 v[34:35], v[68:69], v[36:37] op_sel_hi:[0,1]
	v_and_b32_sdwa v36, v51, v184 dst_sel:DWORD dst_unused:UNUSED_PAD src0_sel:WORD_1 src1_sel:DWORD
	v_and_b32_sdwa v37, v50, v184 dst_sel:DWORD dst_unused:UNUSED_PAD src0_sel:WORD_1 src1_sel:DWORD
	v_add3_u32 v37, v50, v37, s54
	v_add3_u32 v36, v51, v36, s54
	v_and_b32_sdwa v50, v35, v184 dst_sel:DWORD dst_unused:UNUSED_PAD src0_sel:WORD_1 src1_sel:DWORD
	v_and_b32_sdwa v51, v34, v184 dst_sel:DWORD dst_unused:UNUSED_PAD src0_sel:WORD_1 src1_sel:DWORD
	v_add3_u32 v35, v35, v50, s54
	v_add3_u32 v34, v34, v51, s54
	v_and_b32_e32 v35, 0xffff0000, v35
	v_and_b32_e32 v34, 0xffff0000, v34
	v_or_b32_sdwa v35, v35, v36 dst_sel:DWORD dst_unused:UNUSED_PAD src0_sel:DWORD src1_sel:WORD_1
	v_or_b32_sdwa v34, v34, v37 dst_sel:DWORD dst_unused:UNUSED_PAD src0_sel:DWORD src1_sel:WORD_1
	global_store_dwordx2 v[66:67], v[34:35], off offset:64
; #define GAS __attribute__((address_space(1)))
; __device__ __forceinline__ unsigned pk2(float lo, float hi) { return f2bf(lo) | (f2bf(hi) << 16); }
; template <int NT>
; __device__ __forceinline__ void attn_qtile(const LAS unsigned char* lds, int ktile0, const bf16x8 (&Q)[8], int r, int kmin, int kmax, int g, float sink, bf16* orow, int lane) {
;     ...
; #pragma unroll
;     for (int dt = 0; dt < 4; ++dt)
; #pragma unroll
;         for (int i = 0; i < 4; ++i) { v2u w; w.x = pk2(O[dt][4 * i + 0] * inv, O[dt][4 * i + 1] * inv); w.y = pk2(O[dt][4 * i + 2] * inv, O[dt][4 * i + 3] * inv);
;             *(GAS v2u*)(orow + 32 * dt + 8 * i + 4 * h) = w; }
	v_mov_b32_e32 v34, v38
	v_mov_b32_e32 v35, v40
	v_pk_mul_f32 v[34:35], v[68:69], v[34:35] op_sel_hi:[0,1]
	v_mov_b32_e32 v40, v39
	v_pk_mul_f32 v[36:37], v[68:69], v[40:41] op_sel_hi:[0,1]
	v_and_b32_sdwa v38, v35, v184 dst_sel:DWORD dst_unused:UNUSED_PAD src0_sel:WORD_1 src1_sel:DWORD
	v_and_b32_sdwa v39, v34, v184 dst_sel:DWORD dst_unused:UNUSED_PAD src0_sel:WORD_1 src1_sel:DWORD
	v_add3_u32 v34, v34, v39, s54
	v_add3_u32 v35, v35, v38, s54
	v_and_b32_sdwa v38, v37, v184 dst_sel:DWORD dst_unused:UNUSED_PAD src0_sel:WORD_1 src1_sel:DWORD
	v_and_b32_sdwa v39, v36, v184 dst_sel:DWORD dst_unused:UNUSED_PAD src0_sel:WORD_1 src1_sel:DWORD
	v_add3_u32 v37, v37, v38, s54
	v_add3_u32 v36, v36, v39, s54
	v_and_b32_e32 v37, 0xffff0000, v37
	v_and_b32_e32 v36, 0xffff0000, v36
	v_or_b32_sdwa v35, v37, v35 dst_sel:DWORD dst_unused:UNUSED_PAD src0_sel:DWORD src1_sel:WORD_1
	v_or_b32_sdwa v34, v36, v34 dst_sel:DWORD dst_unused:UNUSED_PAD src0_sel:DWORD src1_sel:WORD_1
	global_store_dwordx2 v[66:67], v[34:35], off offset:80
	v_mov_b32_e32 v34, v42
	v_mov_b32_e32 v35, v44
	v_pk_mul_f32 v[34:35], v[68:69], v[34:35] op_sel_hi:[0,1]
	v_mov_b32_e32 v44, v43
	v_pk_mul_f32 v[36:37], v[68:69], v[44:45] op_sel_hi:[0,1]
	v_and_b32_sdwa v38, v35, v184 dst_sel:DWORD dst_unused:UNUSED_PAD src0_sel:WORD_1 src1_sel:DWORD
	v_and_b32_sdwa v39, v34, v184 dst_sel:DWORD dst_unused:UNUSED_PAD src0_sel:WORD_1 src1_sel:DWORD
	v_add3_u32 v34, v34, v39, s54
	v_add3_u32 v35, v35, v38, s54
	v_and_b32_sdwa v38, v37, v184 dst_sel:DWORD dst_unused:UNUSED_PAD src0_sel:WORD_1 src1_sel:DWORD
	v_and_b32_sdwa v39, v36, v184 dst_sel:DWORD dst_unused:UNUSED_PAD src0_sel:WORD_1 src1_sel:DWORD
	v_add3_u32 v37, v37, v38, s54
	v_add3_u32 v36, v36, v39, s54
	v_and_b32_e32 v37, 0xffff0000, v37
	v_and_b32_e32 v36, 0xffff0000, v36
	v_or_b32_sdwa v35, v37, v35 dst_sel:DWORD dst_unused:UNUSED_PAD src0_sel:DWORD src1_sel:WORD_1
	v_or_b32_sdwa v34, v36, v34 dst_sel:DWORD dst_unused:UNUSED_PAD src0_sel:DWORD src1_sel:WORD_1
	global_store_dwordx2 v[66:67], v[34:35], off offset:96
	v_mov_b32_e32 v34, v46
	v_mov_b32_e32 v35, v48
	v_pk_mul_f32 v[34:35], v[68:69], v[34:35] op_sel_hi:[0,1]
	v_mov_b32_e32 v48, v47
	v_pk_mul_f32 v[36:37], v[68:69], v[48:49] op_sel_hi:[0,1]
	v_and_b32_sdwa v38, v35, v184 dst_sel:DWORD dst_unused:UNUSED_PAD src0_sel:WORD_1 src1_sel:DWORD
	v_and_b32_sdwa v39, v34, v184 dst_sel:DWORD dst_unused:UNUSED_PAD src0_sel:WORD_1 src1_sel:DWORD
	v_add3_u32 v34, v34, v39, s54
	v_add3_u32 v35, v35, v38, s54
	v_and_b32_sdwa v38, v37, v184 dst_sel:DWORD dst_unused:UNUSED_PAD src0_sel:WORD_1 src1_sel:DWORD
	v_and_b32_sdwa v39, v36, v184 dst_sel:DWORD dst_unused:UNUSED_PAD src0_sel:WORD_1 src1_sel:DWORD
	v_add3_u32 v37, v37, v38, s54
	v_add3_u32 v36, v36, v39, s54
	v_and_b32_e32 v37, 0xffff0000, v37
	v_and_b32_e32 v36, 0xffff0000, v36
	v_or_b32_sdwa v35, v37, v35 dst_sel:DWORD dst_unused:UNUSED_PAD src0_sel:DWORD src1_sel:WORD_1
	v_or_b32_sdwa v34, v36, v34 dst_sel:DWORD dst_unused:UNUSED_PAD src0_sel:DWORD src1_sel:WORD_1
	global_store_dwordx2 v[66:67], v[34:35], off offset:112
	v_mov_b32_e32 v34, v18
	v_mov_b32_e32 v35, v20
	v_pk_mul_f32 v[34:35], v[68:69], v[34:35] op_sel_hi:[0,1]
	v_mov_b32_e32 v20, v19
	v_pk_mul_f32 v[18:19], v[68:69], v[20:21] op_sel_hi:[0,1]
	v_and_b32_sdwa v20, v35, v184 dst_sel:DWORD dst_unused:UNUSED_PAD src0_sel:WORD_1 src1_sel:DWORD
	v_and_b32_sdwa v21, v34, v184 dst_sel:DWORD dst_unused:UNUSED_PAD src0_sel:WORD_1 src1_sel:DWORD
	v_add3_u32 v21, v34, v21, s54
	v_add3_u32 v20, v35, v20, s54
	v_and_b32_sdwa v34, v19, v184 dst_sel:DWORD dst_unused:UNUSED_PAD src0_sel:WORD_1 src1_sel:DWORD
	v_and_b32_sdwa v35, v18, v184 dst_sel:DWORD dst_unused:UNUSED_PAD src0_sel:WORD_1 src1_sel:DWORD
	v_add3_u32 v19, v19, v34, s54
	v_add3_u32 v18, v18, v35, s54
	v_and_b32_e32 v19, 0xffff0000, v19
	v_and_b32_e32 v18, 0xffff0000, v18
	v_or_b32_sdwa v19, v19, v20 dst_sel:DWORD dst_unused:UNUSED_PAD src0_sel:DWORD src1_sel:WORD_1
	v_or_b32_sdwa v18, v18, v21 dst_sel:DWORD dst_unused:UNUSED_PAD src0_sel:DWORD src1_sel:WORD_1
	global_store_dwordx2 v[66:67], v[18:19], off offset:128
	v_mov_b32_e32 v18, v22
	v_mov_b32_e32 v19, v24
	v_pk_mul_f32 v[18:19], v[68:69], v[18:19] op_sel_hi:[0,1]
	v_mov_b32_e32 v24, v23
	v_pk_mul_f32 v[20:21], v[68:69], v[24:25] op_sel_hi:[0,1]
	v_and_b32_sdwa v22, v19, v184 dst_sel:DWORD dst_unused:UNUSED_PAD src0_sel:WORD_1 src1_sel:DWORD
	v_and_b32_sdwa v23, v18, v184 dst_sel:DWORD dst_unused:UNUSED_PAD src0_sel:WORD_1 src1_sel:DWORD
	v_add3_u32 v18, v18, v23, s54
	v_add3_u32 v19, v19, v22, s54
	v_and_b32_sdwa v22, v21, v184 dst_sel:DWORD dst_unused:UNUSED_PAD src0_sel:WORD_1 src1_sel:DWORD
	v_and_b32_sdwa v23, v20, v184 dst_sel:DWORD dst_unused:UNUSED_PAD src0_sel:WORD_1 src1_sel:DWORD
	v_add3_u32 v21, v21, v22, s54
	v_add3_u32 v20, v20, v23, s54
	v_and_b32_e32 v21, 0xffff0000, v21
	v_and_b32_e32 v20, 0xffff0000, v20
	v_or_b32_sdwa v19, v21, v19 dst_sel:DWORD dst_unused:UNUSED_PAD src0_sel:DWORD src1_sel:WORD_1
	v_or_b32_sdwa v18, v20, v18 dst_sel:DWORD dst_unused:UNUSED_PAD src0_sel:DWORD src1_sel:WORD_1
	global_store_dwordx2 v[66:67], v[18:19], off offset:144
	v_mov_b32_e32 v18, v26
	v_mov_b32_e32 v19, v28
	v_pk_mul_f32 v[18:19], v[68:69], v[18:19] op_sel_hi:[0,1]
	v_mov_b32_e32 v28, v27
	v_pk_mul_f32 v[20:21], v[68:69], v[28:29] op_sel_hi:[0,1]
	v_and_b32_sdwa v22, v19, v184 dst_sel:DWORD dst_unused:UNUSED_PAD src0_sel:WORD_1 src1_sel:DWORD
	v_and_b32_sdwa v23, v18, v184 dst_sel:DWORD dst_unused:UNUSED_PAD src0_sel:WORD_1 src1_sel:DWORD
	v_add3_u32 v18, v18, v23, s54
	v_add3_u32 v19, v19, v22, s54
	v_and_b32_sdwa v22, v21, v184 dst_sel:DWORD dst_unused:UNUSED_PAD src0_sel:WORD_1 src1_sel:DWORD
; #define GAS __attribute__((address_space(1)))
; __device__ __forceinline__ unsigned pk2(float lo, float hi) { return f2bf(lo) | (f2bf(hi) << 16); }
; template <int NT>
; __device__ __forceinline__ void attn_qtile(const LAS unsigned char* lds, int ktile0, const bf16x8 (&Q)[8], int r, int kmin, int kmax, int g, float sink, bf16* orow, int lane) {
;     ...
; #pragma unroll
;     for (int dt = 0; dt < 4; ++dt)
; #pragma unroll
;         for (int i = 0; i < 4; ++i) { v2u w; w.x = pk2(O[dt][4 * i + 0] * inv, O[dt][4 * i + 1] * inv); w.y = pk2(O[dt][4 * i + 2] * inv, O[dt][4 * i + 3] * inv);
;             *(GAS v2u*)(orow + 32 * dt + 8 * i + 4 * h) = w; }
; __device__ __forceinline__ void prompt_unit(Frame& F, const Args& A, int b, int hk) {
;     ...
; #pragma unroll 1
;     for (int qt = 0; qt < 2; ++qt) { const int r = 64 * half + 32 * qt + c, row = 128 * b + r;
;         bf16x8 Q[8];
; #pragma unroll
;         for (int ks = 0; ks < 8; ++ks) Q[ks] = *(const GAS bf16x8*)(PROJ + (size_t)row * NPROJ + 128 * head + 16 * ks + 8 * h);
;         attn_qtile<5>(lds, 2 * half + qt, Q, r, b == 0 ? 128 : 0, 256, g, sink, MIX + (size_t)row * D + 128 * head, F.lane);
;     }
;     __syncthreads();
	v_and_b32_sdwa v23, v20, v184 dst_sel:DWORD dst_unused:UNUSED_PAD src0_sel:WORD_1 src1_sel:DWORD
	v_add3_u32 v21, v21, v22, s54
	v_add3_u32 v20, v20, v23, s54
	v_and_b32_e32 v21, 0xffff0000, v21
	v_and_b32_e32 v20, 0xffff0000, v20
	v_or_b32_sdwa v19, v21, v19 dst_sel:DWORD dst_unused:UNUSED_PAD src0_sel:DWORD src1_sel:WORD_1
	v_or_b32_sdwa v18, v20, v18 dst_sel:DWORD dst_unused:UNUSED_PAD src0_sel:DWORD src1_sel:WORD_1
	global_store_dwordx2 v[66:67], v[18:19], off offset:160
	v_mov_b32_e32 v18, v30
	v_mov_b32_e32 v19, v32
	v_pk_mul_f32 v[18:19], v[68:69], v[18:19] op_sel_hi:[0,1]
	v_mov_b32_e32 v32, v31
	v_pk_mul_f32 v[20:21], v[68:69], v[32:33] op_sel_hi:[0,1]
	v_and_b32_sdwa v22, v19, v184 dst_sel:DWORD dst_unused:UNUSED_PAD src0_sel:WORD_1 src1_sel:DWORD
	v_and_b32_sdwa v23, v18, v184 dst_sel:DWORD dst_unused:UNUSED_PAD src0_sel:WORD_1 src1_sel:DWORD
	v_add3_u32 v18, v18, v23, s54
	v_add3_u32 v19, v19, v22, s54
	v_and_b32_sdwa v22, v21, v184 dst_sel:DWORD dst_unused:UNUSED_PAD src0_sel:WORD_1 src1_sel:DWORD
	v_and_b32_sdwa v23, v20, v184 dst_sel:DWORD dst_unused:UNUSED_PAD src0_sel:WORD_1 src1_sel:DWORD
	v_add3_u32 v21, v21, v22, s54
	v_add3_u32 v20, v20, v23, s54
	v_and_b32_e32 v21, 0xffff0000, v21
	v_and_b32_e32 v20, 0xffff0000, v20
	v_or_b32_sdwa v19, v21, v19 dst_sel:DWORD dst_unused:UNUSED_PAD src0_sel:DWORD src1_sel:WORD_1
	v_or_b32_sdwa v18, v20, v18 dst_sel:DWORD dst_unused:UNUSED_PAD src0_sel:DWORD src1_sel:WORD_1
	global_store_dwordx2 v[66:67], v[18:19], off offset:176
	v_mov_b32_e32 v18, v2
	v_mov_b32_e32 v19, v4
	v_pk_mul_f32 v[18:19], v[68:69], v[18:19] op_sel_hi:[0,1]
	v_mov_b32_e32 v4, v3
	v_pk_mul_f32 v[2:3], v[68:69], v[4:5] op_sel_hi:[0,1]
	v_and_b32_sdwa v4, v19, v184 dst_sel:DWORD dst_unused:UNUSED_PAD src0_sel:WORD_1 src1_sel:DWORD
	v_and_b32_sdwa v5, v18, v184 dst_sel:DWORD dst_unused:UNUSED_PAD src0_sel:WORD_1 src1_sel:DWORD
	v_add3_u32 v5, v18, v5, s54
	v_add3_u32 v4, v19, v4, s54
	v_and_b32_sdwa v18, v3, v184 dst_sel:DWORD dst_unused:UNUSED_PAD src0_sel:WORD_1 src1_sel:DWORD
	v_and_b32_sdwa v19, v2, v184 dst_sel:DWORD dst_unused:UNUSED_PAD src0_sel:WORD_1 src1_sel:DWORD
	v_add3_u32 v3, v3, v18, s54
	v_add3_u32 v2, v2, v19, s54
	v_and_b32_e32 v3, 0xffff0000, v3
	v_and_b32_e32 v2, 0xffff0000, v2
	v_or_b32_sdwa v3, v3, v4 dst_sel:DWORD dst_unused:UNUSED_PAD src0_sel:DWORD src1_sel:WORD_1
	v_or_b32_sdwa v2, v2, v5 dst_sel:DWORD dst_unused:UNUSED_PAD src0_sel:DWORD src1_sel:WORD_1
	global_store_dwordx2 v[66:67], v[2:3], off offset:192
	v_mov_b32_e32 v2, v6
	v_mov_b32_e32 v3, v8
	v_pk_mul_f32 v[2:3], v[68:69], v[2:3] op_sel_hi:[0,1]
	v_mov_b32_e32 v8, v7
	v_pk_mul_f32 v[4:5], v[68:69], v[8:9] op_sel_hi:[0,1]
	v_and_b32_sdwa v6, v3, v184 dst_sel:DWORD dst_unused:UNUSED_PAD src0_sel:WORD_1 src1_sel:DWORD
	v_and_b32_sdwa v7, v2, v184 dst_sel:DWORD dst_unused:UNUSED_PAD src0_sel:WORD_1 src1_sel:DWORD
	v_add3_u32 v2, v2, v7, s54
	v_add3_u32 v3, v3, v6, s54
	v_and_b32_sdwa v6, v5, v184 dst_sel:DWORD dst_unused:UNUSED_PAD src0_sel:WORD_1 src1_sel:DWORD
	v_and_b32_sdwa v7, v4, v184 dst_sel:DWORD dst_unused:UNUSED_PAD src0_sel:WORD_1 src1_sel:DWORD
	v_add3_u32 v5, v5, v6, s54
	v_add3_u32 v4, v4, v7, s54
	v_and_b32_e32 v5, 0xffff0000, v5
	v_and_b32_e32 v4, 0xffff0000, v4
	v_or_b32_sdwa v3, v5, v3 dst_sel:DWORD dst_unused:UNUSED_PAD src0_sel:DWORD src1_sel:WORD_1
	v_or_b32_sdwa v2, v4, v2 dst_sel:DWORD dst_unused:UNUSED_PAD src0_sel:DWORD src1_sel:WORD_1
	global_store_dwordx2 v[66:67], v[2:3], off offset:208
	v_mov_b32_e32 v2, v10
	v_mov_b32_e32 v3, v12
	v_pk_mul_f32 v[2:3], v[68:69], v[2:3] op_sel_hi:[0,1]
	v_mov_b32_e32 v12, v11
	v_pk_mul_f32 v[4:5], v[68:69], v[12:13] op_sel_hi:[0,1]
	v_and_b32_sdwa v6, v3, v184 dst_sel:DWORD dst_unused:UNUSED_PAD src0_sel:WORD_1 src1_sel:DWORD
	v_and_b32_sdwa v7, v2, v184 dst_sel:DWORD dst_unused:UNUSED_PAD src0_sel:WORD_1 src1_sel:DWORD
	v_add3_u32 v2, v2, v7, s54
	v_add3_u32 v3, v3, v6, s54
	v_and_b32_sdwa v6, v5, v184 dst_sel:DWORD dst_unused:UNUSED_PAD src0_sel:WORD_1 src1_sel:DWORD
	v_and_b32_sdwa v7, v4, v184 dst_sel:DWORD dst_unused:UNUSED_PAD src0_sel:WORD_1 src1_sel:DWORD
	v_add3_u32 v5, v5, v6, s54
	v_add3_u32 v4, v4, v7, s54
	v_and_b32_e32 v5, 0xffff0000, v5
	v_and_b32_e32 v4, 0xffff0000, v4
	v_or_b32_sdwa v3, v5, v3 dst_sel:DWORD dst_unused:UNUSED_PAD src0_sel:DWORD src1_sel:WORD_1
	v_or_b32_sdwa v2, v4, v2 dst_sel:DWORD dst_unused:UNUSED_PAD src0_sel:DWORD src1_sel:WORD_1
	global_store_dwordx2 v[66:67], v[2:3], off offset:224
	v_mov_b32_e32 v2, v14
	v_mov_b32_e32 v3, v16
	v_pk_mul_f32 v[2:3], v[68:69], v[2:3] op_sel_hi:[0,1]
	v_mov_b32_e32 v16, v15
	v_pk_mul_f32 v[4:5], v[68:69], v[16:17] op_sel_hi:[0,1]
	v_and_b32_sdwa v6, v3, v184 dst_sel:DWORD dst_unused:UNUSED_PAD src0_sel:WORD_1 src1_sel:DWORD
	v_and_b32_sdwa v7, v2, v184 dst_sel:DWORD dst_unused:UNUSED_PAD src0_sel:WORD_1 src1_sel:DWORD
	v_add3_u32 v2, v2, v7, s54
	v_add3_u32 v3, v3, v6, s54
	v_and_b32_sdwa v6, v5, v184 dst_sel:DWORD dst_unused:UNUSED_PAD src0_sel:WORD_1 src1_sel:DWORD
	v_and_b32_sdwa v7, v4, v184 dst_sel:DWORD dst_unused:UNUSED_PAD src0_sel:WORD_1 src1_sel:DWORD
	v_add3_u32 v5, v5, v6, s54
	v_add3_u32 v4, v4, v7, s54
	v_and_b32_e32 v5, 0xffff0000, v5
	v_and_b32_e32 v4, 0xffff0000, v4
	v_or_b32_sdwa v3, v5, v3 dst_sel:DWORD dst_unused:UNUSED_PAD src0_sel:DWORD src1_sel:WORD_1
	v_or_b32_sdwa v2, v4, v2 dst_sel:DWORD dst_unused:UNUSED_PAD src0_sel:DWORD src1_sel:WORD_1
	s_and_b64 vcc, exec, s[10:11]
	s_mov_b64 s[10:11], 0
	global_store_dwordx2 v[66:67], v[2:3], off offset:240
	s_cbranch_vccnz .LBB0_625
	s_add_i32 s55, s55, s33
	s_cmpk_gt_i32 s55, 0xff
	s_barrier
	s_cbranch_scc0 .LBB0_609
